# GEMM load phases: vmcnt(8) and lgkmcnt(0) waits merged into one s_waitcnt
# baseline (speedup 1.0000x reference)
; #define PG8_STAGE(bufoff, gbase, voff) do { _Pragma("unroll") for (int _i = 0; _i < 2; ++_i) \
;         __builtin_amdgcn_global_load_lds((const unsigned*)((const char*)(gbase) + (voff)[_i]), (LAS unsigned*)(lds + (bufoff) + ldsw + _i * 8192), 16, 0, 0); } while (0)
; #define PG8_LDA(dst, b, h) do { _Pragma("unroll") for (int m = 0; m < 4; ++m) _Pragma("unroll") for (int k = 0; k < 2; ++k) dst[m][k] = *(const LAS bf16x8*)(lds + PG8_SA(b, h) + aoff + m * 2048 + k * 1024); } while (0)
; #define PG8_LDB(dst, b, h) do { _Pragma("unroll") for (int n = 0; n < 2; ++n) _Pragma("unroll") for (int k = 0; k < 2; ++k) dst[n][k] = *(const LAS bf16x8*)(lds + PG8_SB(b, h) + boff + n * 2048 + k * 1024); } while (0)
; #define PG8_MMA(ai, bj, At, Bt) do { __builtin_amdgcn_s_setprio(1); _Pragma("unroll") for (int m = 0; m < 4; ++m) _Pragma("unroll") for (int n = 0; n < 2; ++n) _Pragma("unroll") for (int k = 0; k < 2; ++k) \
;         acc[ai][bj][m][n] = __builtin_amdgcn_mfma_f32_16x16x32_bf16(Bt[n][k], At[m][k], acc[ai][bj][m][n], 0, 0, 0); __builtin_amdgcn_s_setprio(0); } while (0)
; #define PG8_WAIT_V(n) asm volatile("s_waitcnt vmcnt(" #n ")" ::: "memory")
; #define PG8_WAIT_L(n) asm volatile("s_waitcnt lgkmcnt(" #n ")" ::: "memory")
; #define PG8_BAR __builtin_amdgcn_s_barrier()
; #define PG8_SCHED __builtin_amdgcn_sched_barrier(0)
; template <class Epi, class Sched>
; __device__ __forceinline__ void gemm_phase(LAS unsigned char* lds, const int lda, const int ldb, const int K, const Sched& S, const Epi& E, int tid) {
;     ...
;             const bool last = (t == nt - 2);
;             const char* a1 = cA + (size_t)(t + 1) * kstep;
;             const char* a2 = last ? nA : cA + (size_t)(t + 2) * kstep; const char* b2 = last ? nB : cB + (size_t)(t + 2) * kstep;
;             const char* a3 = a2 + kstep; const char* b3 = b2 + kstep;
;             PG8_LDB(B0, 0, 0); PG8_LDB(B1, 0, 1); PG8_SCHED; PG8_LDA(At, 0, 0); PG8_STAGE(PG8_SA(1, 1), a1 + hA, voffA);
;             PG8_WAIT_V(8); PG8_WAIT_L(0); PG8_BAR; PG8_MMA(0, 0, At, B0); PG8_MMA(0, 1, At, B1); PG8_BAR; PG8_SCHED;
;             PG8_LDA(At, 0, 1); PG8_STAGE(PG8_SB(0, 0), b2, voffB); PG8_STAGE(PG8_SB(0, 1), b2 + hB, voffB); PG8_STAGE(PG8_SA(0, 0), a2, voffA);
;             PG8_WAIT_V(8); PG8_WAIT_L(0); PG8_BAR; PG8_MMA(1, 0, At, B0); PG8_MMA(1, 1, At, B1); PG8_BAR; PG8_SCHED;
.LBB0_91:
	s_add_u32 s10, s4, 0xfff80080
	s_addc_u32 s11, s5, -1
	s_add_i32 s22, 0, 0x10000
	s_cmp_eq_u32 s18, 28
	s_cselect_b32 s17, s3, s11
	s_cselect_b32 s16, s2, s10
	v_add_u32_e32 v0, s22, v174
	s_cselect_b32 s11, s15, s9
	s_cselect_b32 s10, s14, s7
	s_add_i32 s33, 0, 0x14000
	ds_read_b128 v[130:133], v0
	ds_read_b128 v[134:137], v0 offset:1024
	ds_read_b128 v[138:141], v0 offset:2048
	ds_read_b128 v[142:145], v0 offset:3072
	v_add_u32_e32 v0, s33, v174
	ds_read_b128 v[160:163], v0
	ds_read_b128 v[164:167], v0 offset:1024
	ds_read_b128 v[168:171], v0 offset:2048
	ds_read_b128 v[180:183], v0 offset:3072
	s_add_i32 m0, s21, 0xc000
	ds_read_b128 v[184:187], v178
	ds_read_b128 v[188:191], v178 offset:1024
	ds_read_b128 v[192:195], v178 offset:2048
	ds_read_b128 v[200:203], v178 offset:3072
	ds_read_b128 v[204:207], v178 offset:4096
	ds_read_b128 v[208:211], v178 offset:5120
	ds_read_b128 v[212:215], v178 offset:6144
	ds_read_b128 v[216:219], v178 offset:7168
	global_load_lds_dwordx4 v156, s[4:5]
	s_add_i32 m0, s21, 0xe000
	s_nop 0
	global_load_lds_dwordx4 v158, s[4:5]
	s_waitcnt vmcnt(8) lgkmcnt(0)
	s_barrier
	s_setprio 1
	v_mfma_f32_16x16x32_bf16 v[126:129], v[130:133], v[184:187], v[126:129]
	v_mfma_f32_16x16x32_bf16 v[122:125], v[138:141], v[184:187], v[122:125]
	v_mfma_f32_16x16x32_bf16 v[118:121], v[130:133], v[192:195], v[118:121]
	v_mfma_f32_16x16x32_bf16 v[110:113], v[138:141], v[192:195], v[110:113]
	v_mfma_f32_16x16x32_bf16 v[102:105], v[130:133], v[204:207], v[102:105]
	v_mfma_f32_16x16x32_bf16 v[94:97], v[138:141], v[204:207], v[94:97]
	v_mfma_f32_16x16x32_bf16 v[86:89], v[130:133], v[212:215], v[86:89]
	v_mfma_f32_16x16x32_bf16 v[78:81], v[138:141], v[212:215], v[78:81]
	v_mfma_f32_16x16x32_bf16 v[126:129], v[134:137], v[188:191], v[126:129]
	v_mfma_f32_16x16x32_bf16 v[122:125], v[142:145], v[188:191], v[122:125]
	v_mfma_f32_16x16x32_bf16 v[118:121], v[134:137], v[200:203], v[118:121]
	v_mfma_f32_16x16x32_bf16 v[110:113], v[142:145], v[200:203], v[110:113]
	v_mfma_f32_16x16x32_bf16 v[102:105], v[134:137], v[208:211], v[102:105]
	v_mfma_f32_16x16x32_bf16 v[94:97], v[142:145], v[208:211], v[94:97]
	v_mfma_f32_16x16x32_bf16 v[86:89], v[134:137], v[216:219], v[86:89]
	v_mfma_f32_16x16x32_bf16 v[78:81], v[142:145], v[216:219], v[78:81]
	s_setprio 0
	s_setprio 1
	v_mfma_f32_16x16x32_bf16 v[114:117], v[160:163], v[184:187], v[114:117]
	v_mfma_f32_16x16x32_bf16 v[106:109], v[168:171], v[184:187], v[106:109]
	v_mfma_f32_16x16x32_bf16 v[98:101], v[160:163], v[192:195], v[98:101]
	v_mfma_f32_16x16x32_bf16 v[90:93], v[168:171], v[192:195], v[90:93]
	v_mfma_f32_16x16x32_bf16 v[82:85], v[160:163], v[204:207], v[82:85]
	v_mfma_f32_16x16x32_bf16 v[74:77], v[168:171], v[204:207], v[74:77]
	v_mfma_f32_16x16x32_bf16 v[70:73], v[160:163], v[212:215], v[70:73]
	v_mfma_f32_16x16x32_bf16 v[66:69], v[168:171], v[212:215], v[66:69]
	v_mfma_f32_16x16x32_bf16 v[114:117], v[164:167], v[188:191], v[114:117]
	v_mfma_f32_16x16x32_bf16 v[106:109], v[180:183], v[188:191], v[106:109]
	v_mfma_f32_16x16x32_bf16 v[98:101], v[164:167], v[200:203], v[98:101]
	v_mfma_f32_16x16x32_bf16 v[90:93], v[180:183], v[200:203], v[90:93]
	v_mfma_f32_16x16x32_bf16 v[82:85], v[164:167], v[208:211], v[82:85]
	v_mfma_f32_16x16x32_bf16 v[74:77], v[180:183], v[208:211], v[74:77]
	v_mfma_f32_16x16x32_bf16 v[70:73], v[164:167], v[216:219], v[70:73]
	v_mfma_f32_16x16x32_bf16 v[66:69], v[180:183], v[216:219], v[66:69]
	s_setprio 0
	s_barrier
	s_add_u32 s98, s10, s30
	s_addc_u32 s99, s11, s31
	s_add_u32 s100, s16, s30
	s_addc_u32 s101, s17, s31
	s_add_i32 s22, s22, s20
	s_mov_b32 m0, s22
	ds_read_b128 v[184:187], v178 offset:16384
	ds_read_b128 v[188:191], v178 offset:17408
	ds_read_b128 v[192:195], v178 offset:18432
	ds_read_b128 v[200:203], v178 offset:19456
	ds_read_b128 v[204:207], v178 offset:20480
	ds_read_b128 v[208:211], v178 offset:21504
	ds_read_b128 v[212:215], v178 offset:22528
	ds_read_b128 v[216:219], v178 offset:23552
	global_load_lds_dwordx4 v148, s[10:11]
	s_add_i32 m0, s22, 0x2000
	s_add_u32 s22, s10, 0x80000
	s_addc_u32 s23, s11, 0
	s_add_i32 s33, s33, s20
	global_load_lds_dwordx4 v152, s[10:11]
	s_mov_b32 m0, s33
	s_nop 0
	global_load_lds_dwordx4 v148, s[22:23]
	s_add_i32 m0, s33, 0x2000
	s_nop 0
	global_load_lds_dwordx4 v152, s[22:23]
	s_mov_b32 m0, s21
	s_nop 0
	global_load_lds_dwordx4 v146, s[16:17]
	s_mov_b32 m0, s25
	s_nop 0
	global_load_lds_dwordx4 v150, s[16:17]
	s_waitcnt vmcnt(8) lgkmcnt(0)
	s_barrier
	s_setprio 1
	v_mfma_f32_16x16x32_bf16 v[62:65], v[130:133], v[184:187], v[62:65]
	v_mfma_f32_16x16x32_bf16 v[58:61], v[138:141], v[184:187], v[58:61]
	v_mfma_f32_16x16x32_bf16 v[54:57], v[130:133], v[192:195], v[54:57]
	v_mfma_f32_16x16x32_bf16 v[46:49], v[138:141], v[192:195], v[46:49]
	v_mfma_f32_16x16x32_bf16 v[38:41], v[130:133], v[204:207], v[38:41]
	v_mfma_f32_16x16x32_bf16 v[30:33], v[138:141], v[204:207], v[30:33]
	v_mfma_f32_16x16x32_bf16 v[22:25], v[130:133], v[212:215], v[22:25]
	v_mfma_f32_16x16x32_bf16 v[14:17], v[138:141], v[212:215], v[14:17]
	v_mfma_f32_16x16x32_bf16 v[62:65], v[134:137], v[188:191], v[62:65]
	v_mfma_f32_16x16x32_bf16 v[58:61], v[142:145], v[188:191], v[58:61]
	v_mfma_f32_16x16x32_bf16 v[54:57], v[134:137], v[200:203], v[54:57]
	v_mfma_f32_16x16x32_bf16 v[46:49], v[142:145], v[200:203], v[46:49]
	v_mfma_f32_16x16x32_bf16 v[38:41], v[134:137], v[208:211], v[38:41]
	v_mfma_f32_16x16x32_bf16 v[30:33], v[142:145], v[208:211], v[30:33]
	v_mfma_f32_16x16x32_bf16 v[22:25], v[134:137], v[216:219], v[22:25]
	v_mfma_f32_16x16x32_bf16 v[14:17], v[142:145], v[216:219], v[14:17]
	s_setprio 0
	s_setprio 1
	v_mfma_f32_16x16x32_bf16 v[50:53], v[160:163], v[184:187], v[50:53]
	v_mfma_f32_16x16x32_bf16 v[42:45], v[168:171], v[184:187], v[42:45]
	v_mfma_f32_16x16x32_bf16 v[34:37], v[160:163], v[192:195], v[34:37]
	v_mfma_f32_16x16x32_bf16 v[26:29], v[168:171], v[192:195], v[26:29]
	v_mfma_f32_16x16x32_bf16 v[18:21], v[160:163], v[204:207], v[18:21]
	v_mfma_f32_16x16x32_bf16 v[10:13], v[168:171], v[204:207], v[10:13]
	v_mfma_f32_16x16x32_bf16 v[6:9], v[160:163], v[212:215], v[6:9]
	v_mfma_f32_16x16x32_bf16 v[2:5], v[168:171], v[212:215], v[2:5]
	v_mfma_f32_16x16x32_bf16 v[50:53], v[164:167], v[188:191], v[50:53]
	v_mfma_f32_16x16x32_bf16 v[42:45], v[180:183], v[188:191], v[42:45]
	v_mfma_f32_16x16x32_bf16 v[34:37], v[164:167], v[200:203], v[34:37]
	v_mfma_f32_16x16x32_bf16 v[26:29], v[180:183], v[200:203], v[26:29]
	v_mfma_f32_16x16x32_bf16 v[18:21], v[164:167], v[208:211], v[18:21]
	v_mfma_f32_16x16x32_bf16 v[10:13], v[180:183], v[208:211], v[10:13]
	v_mfma_f32_16x16x32_bf16 v[6:9], v[164:167], v[216:219], v[6:9]
	v_mfma_f32_16x16x32_bf16 v[2:5], v[180:183], v[216:219], v[2:5]
	s_setprio 0
	s_barrier
; #define PG8_STAGE(bufoff, gbase, voff) do { _Pragma("unroll") for (int _i = 0; _i < 2; ++_i) \
;         __builtin_amdgcn_global_load_lds((const unsigned*)((const char*)(gbase) + (voff)[_i]), (LAS unsigned*)(lds + (bufoff) + ldsw + _i * 8192), 16, 0, 0); } while (0)
; #define PG8_LDA(dst, b, h) do { _Pragma("unroll") for (int m = 0; m < 4; ++m) _Pragma("unroll") for (int k = 0; k < 2; ++k) dst[m][k] = *(const LAS bf16x8*)(lds + PG8_SA(b, h) + aoff + m * 2048 + k * 1024); } while (0)
; #define PG8_LDB(dst, b, h) do { _Pragma("unroll") for (int n = 0; n < 2; ++n) _Pragma("unroll") for (int k = 0; k < 2; ++k) dst[n][k] = *(const LAS bf16x8*)(lds + PG8_SB(b, h) + boff + n * 2048 + k * 1024); } while (0)
; #define PG8_MMA(ai, bj, At, Bt) do { __builtin_amdgcn_s_setprio(1); _Pragma("unroll") for (int m = 0; m < 4; ++m) _Pragma("unroll") for (int n = 0; n < 2; ++n) _Pragma("unroll") for (int k = 0; k < 2; ++k) \
;         acc[ai][bj][m][n] = __builtin_amdgcn_mfma_f32_16x16x32_bf16(Bt[n][k], At[m][k], acc[ai][bj][m][n], 0, 0, 0); __builtin_amdgcn_s_setprio(0); } while (0)
; #define PG8_WAIT_V(n) asm volatile("s_waitcnt vmcnt(" #n ")" ::: "memory")
; #define PG8_WAIT_L(n) asm volatile("s_waitcnt lgkmcnt(" #n ")" ::: "memory")
; #define PG8_BAR __builtin_amdgcn_s_barrier()
; #define PG8_SCHED __builtin_amdgcn_sched_barrier(0)
; template <class Epi, class Sched>
; __device__ __forceinline__ void gemm_phase(LAS unsigned char* lds, const int lda, const int ldb, const int K, const Sched& S, const Epi& E, int tid) {
;     ...
;             PG8_LDB(B0, 1, 0); PG8_LDB(B1, 1, 1); PG8_SCHED; PG8_LDA(At, 1, 0); PG8_STAGE(PG8_SA(0, 1), a2 + hA, voffA);
;             PG8_WAIT_V(8); PG8_WAIT_L(0); PG8_BAR; PG8_MMA(0, 0, At, B0); PG8_MMA(0, 1, At, B1); PG8_BAR; PG8_SCHED;
;             PG8_LDA(At, 1, 1); PG8_STAGE(PG8_SB(1, 0), b3, voffB); PG8_STAGE(PG8_SB(1, 1), b3 + hB, voffB); PG8_STAGE(PG8_SA(1, 0), a3, voffA);
;             PG8_WAIT_V(8); PG8_WAIT_L(0); PG8_BAR; PG8_MMA(1, 0, At, B0); PG8_MMA(1, 1, At, B1); PG8_BAR; PG8_SCHED;
;         }
;         if (wr == 0) PG8_BAR;
	s_add_i32 s22, 0, 0x18000
	v_add_u32_e32 v0, s22, v174
	s_add_i32 s23, 0, 0x1c000
	ds_read_b128 v[130:133], v0
	ds_read_b128 v[134:137], v0 offset:1024
	ds_read_b128 v[138:141], v0 offset:2048
	ds_read_b128 v[142:145], v0 offset:3072
	v_add_u32_e32 v0, s23, v174
	ds_read_b128 v[160:163], v0
	ds_read_b128 v[164:167], v0 offset:1024
	ds_read_b128 v[168:171], v0 offset:2048
	ds_read_b128 v[180:183], v0 offset:3072
	s_add_u32 s16, s16, 0x80000
	s_addc_u32 s17, s17, 0
	s_mov_b32 m0, s26
	ds_read_b128 v[184:187], v178 offset:32768
	ds_read_b128 v[188:191], v178 offset:33792
	ds_read_b128 v[192:195], v178 offset:34816
	ds_read_b128 v[200:203], v178 offset:35840
	ds_read_b128 v[204:207], v178 offset:36864
	ds_read_b128 v[208:211], v178 offset:37888
	ds_read_b128 v[212:215], v178 offset:38912
	ds_read_b128 v[216:219], v178 offset:39936
	global_load_lds_dwordx4 v146, s[16:17]
	s_mov_b32 m0, s27
	s_nop 0
	global_load_lds_dwordx4 v150, s[16:17]
	s_waitcnt vmcnt(8) lgkmcnt(0)
	s_barrier
	s_setprio 1
	v_mfma_f32_16x16x32_bf16 v[126:129], v[130:133], v[184:187], v[126:129]
	v_mfma_f32_16x16x32_bf16 v[122:125], v[138:141], v[184:187], v[122:125]
	v_mfma_f32_16x16x32_bf16 v[118:121], v[130:133], v[192:195], v[118:121]
	v_mfma_f32_16x16x32_bf16 v[110:113], v[138:141], v[192:195], v[110:113]
	v_mfma_f32_16x16x32_bf16 v[102:105], v[130:133], v[204:207], v[102:105]
	v_mfma_f32_16x16x32_bf16 v[94:97], v[138:141], v[204:207], v[94:97]
	v_mfma_f32_16x16x32_bf16 v[86:89], v[130:133], v[212:215], v[86:89]
	v_mfma_f32_16x16x32_bf16 v[78:81], v[138:141], v[212:215], v[78:81]
	v_mfma_f32_16x16x32_bf16 v[126:129], v[134:137], v[188:191], v[126:129]
	v_mfma_f32_16x16x32_bf16 v[122:125], v[142:145], v[188:191], v[122:125]
	v_mfma_f32_16x16x32_bf16 v[118:121], v[134:137], v[200:203], v[118:121]
	v_mfma_f32_16x16x32_bf16 v[110:113], v[142:145], v[200:203], v[110:113]
	v_mfma_f32_16x16x32_bf16 v[102:105], v[134:137], v[208:211], v[102:105]
	v_mfma_f32_16x16x32_bf16 v[94:97], v[142:145], v[208:211], v[94:97]
	v_mfma_f32_16x16x32_bf16 v[86:89], v[134:137], v[216:219], v[86:89]
	v_mfma_f32_16x16x32_bf16 v[78:81], v[142:145], v[216:219], v[78:81]
	s_setprio 0
	s_setprio 1
	v_mfma_f32_16x16x32_bf16 v[114:117], v[160:163], v[184:187], v[114:117]
	v_mfma_f32_16x16x32_bf16 v[106:109], v[168:171], v[184:187], v[106:109]
	v_mfma_f32_16x16x32_bf16 v[98:101], v[160:163], v[192:195], v[98:101]
	v_mfma_f32_16x16x32_bf16 v[90:93], v[168:171], v[192:195], v[90:93]
	v_mfma_f32_16x16x32_bf16 v[82:85], v[160:163], v[204:207], v[82:85]
	v_mfma_f32_16x16x32_bf16 v[74:77], v[168:171], v[204:207], v[74:77]
	v_mfma_f32_16x16x32_bf16 v[70:73], v[160:163], v[212:215], v[70:73]
	v_mfma_f32_16x16x32_bf16 v[66:69], v[168:171], v[212:215], v[66:69]
	v_mfma_f32_16x16x32_bf16 v[114:117], v[164:167], v[188:191], v[114:117]
	v_mfma_f32_16x16x32_bf16 v[106:109], v[180:183], v[188:191], v[106:109]
	v_mfma_f32_16x16x32_bf16 v[98:101], v[164:167], v[200:203], v[98:101]
	v_mfma_f32_16x16x32_bf16 v[90:93], v[180:183], v[200:203], v[90:93]
	v_mfma_f32_16x16x32_bf16 v[82:85], v[164:167], v[208:211], v[82:85]
	v_mfma_f32_16x16x32_bf16 v[74:77], v[180:183], v[208:211], v[74:77]
	v_mfma_f32_16x16x32_bf16 v[70:73], v[164:167], v[216:219], v[70:73]
	v_mfma_f32_16x16x32_bf16 v[66:69], v[180:183], v[216:219], v[66:69]
	s_setprio 0
	s_barrier
	s_add_i32 s16, s22, s20
	s_mov_b32 m0, s16
	ds_read_b128 v[184:187], v178 offset:49152
	ds_read_b128 v[188:191], v178 offset:50176
	ds_read_b128 v[192:195], v178 offset:51200
	ds_read_b128 v[200:203], v178 offset:52224
	ds_read_b128 v[204:207], v178 offset:53248
	ds_read_b128 v[208:211], v178 offset:54272
	ds_read_b128 v[212:215], v178 offset:55296
	ds_read_b128 v[216:219], v178 offset:56320
	global_load_lds_dwordx4 v148, s[98:99]
	s_add_i32 m0, s16, 0x2000
	s_add_u32 s10, s10, 0x80080
	s_addc_u32 s11, s11, 0
	s_add_i32 s16, s23, s20
	global_load_lds_dwordx4 v152, s[98:99]
	s_mov_b32 m0, s16
	s_nop 0
	global_load_lds_dwordx4 v148, s[10:11]
	s_add_i32 m0, s16, 0x2000
	s_nop 0
	global_load_lds_dwordx4 v152, s[10:11]
	s_mov_b32 m0, s54
	s_nop 0
	global_load_lds_dwordx4 v146, s[100:101]
	s_mov_b32 m0, s55
	s_nop 0
	global_load_lds_dwordx4 v150, s[100:101]
	s_waitcnt vmcnt(8) lgkmcnt(0)
	s_barrier
	s_setprio 1
	v_mfma_f32_16x16x32_bf16 v[62:65], v[130:133], v[184:187], v[62:65]
	v_mfma_f32_16x16x32_bf16 v[58:61], v[138:141], v[184:187], v[58:61]
	v_mfma_f32_16x16x32_bf16 v[54:57], v[130:133], v[192:195], v[54:57]
	v_mfma_f32_16x16x32_bf16 v[46:49], v[138:141], v[192:195], v[46:49]
	v_mfma_f32_16x16x32_bf16 v[38:41], v[130:133], v[204:207], v[38:41]
	v_mfma_f32_16x16x32_bf16 v[30:33], v[138:141], v[204:207], v[30:33]
	v_mfma_f32_16x16x32_bf16 v[22:25], v[130:133], v[212:215], v[22:25]
	v_mfma_f32_16x16x32_bf16 v[14:17], v[138:141], v[212:215], v[14:17]
	v_mfma_f32_16x16x32_bf16 v[62:65], v[134:137], v[188:191], v[62:65]
	v_mfma_f32_16x16x32_bf16 v[58:61], v[142:145], v[188:191], v[58:61]
	v_mfma_f32_16x16x32_bf16 v[54:57], v[134:137], v[200:203], v[54:57]
	v_mfma_f32_16x16x32_bf16 v[46:49], v[142:145], v[200:203], v[46:49]
	v_mfma_f32_16x16x32_bf16 v[38:41], v[134:137], v[208:211], v[38:41]
	v_mfma_f32_16x16x32_bf16 v[30:33], v[142:145], v[208:211], v[30:33]
	v_mfma_f32_16x16x32_bf16 v[22:25], v[134:137], v[216:219], v[22:25]
	v_mfma_f32_16x16x32_bf16 v[14:17], v[142:145], v[216:219], v[14:17]
	s_setprio 0
	s_setprio 1
	v_mfma_f32_16x16x32_bf16 v[50:53], v[160:163], v[184:187], v[50:53]
	v_mfma_f32_16x16x32_bf16 v[42:45], v[168:171], v[184:187], v[42:45]
	v_mfma_f32_16x16x32_bf16 v[34:37], v[160:163], v[192:195], v[34:37]
	v_mfma_f32_16x16x32_bf16 v[26:29], v[168:171], v[192:195], v[26:29]
	v_mfma_f32_16x16x32_bf16 v[18:21], v[160:163], v[204:207], v[18:21]
	v_mfma_f32_16x16x32_bf16 v[10:13], v[168:171], v[204:207], v[10:13]
	v_mfma_f32_16x16x32_bf16 v[6:9], v[160:163], v[212:215], v[6:9]
	v_mfma_f32_16x16x32_bf16 v[2:5], v[168:171], v[212:215], v[2:5]
	v_mfma_f32_16x16x32_bf16 v[50:53], v[164:167], v[188:191], v[50:53]
	v_mfma_f32_16x16x32_bf16 v[42:45], v[180:183], v[188:191], v[42:45]
	v_mfma_f32_16x16x32_bf16 v[34:37], v[164:167], v[200:203], v[34:37]
	v_mfma_f32_16x16x32_bf16 v[26:29], v[180:183], v[200:203], v[26:29]
	v_mfma_f32_16x16x32_bf16 v[18:21], v[164:167], v[208:211], v[18:21]
	v_mfma_f32_16x16x32_bf16 v[10:13], v[180:183], v[208:211], v[10:13]
	v_mfma_f32_16x16x32_bf16 v[6:9], v[164:167], v[216:219], v[6:9]
	v_mfma_f32_16x16x32_bf16 v[2:5], v[180:183], v[216:219], v[2:5]
	s_setprio 0
	s_barrier
	s_add_i32 s18, s18, 2
	s_add_u32 s4, s4, 0x100
	s_addc_u32 s5, s5, 0
	s_add_u32 s7, s7, 0x100
	s_addc_u32 s9, s9, 0
	s_cmp_gt_u32 s18, 29
	s_cbranch_scc0 .LBB0_91
	s_and_b64 vcc, exec, s[46:47]
	s_cbranch_vccz .LBB0_94
	s_barrier

; #define PG8_STAGE(bufoff, gbase, voff) do { _Pragma("unroll") for (int _i = 0; _i < 2; ++_i) \
;         __builtin_amdgcn_global_load_lds((const unsigned*)((const char*)(gbase) + (voff)[_i]), (LAS unsigned*)(lds + (bufoff) + ldsw + _i * 8192), 16, 0, 0); } while (0)
; #define PG8_LDA(dst, b, h) do { _Pragma("unroll") for (int m = 0; m < 4; ++m) _Pragma("unroll") for (int k = 0; k < 2; ++k) dst[m][k] = *(const LAS bf16x8*)(lds + PG8_SA(b, h) + aoff + m * 2048 + k * 1024); } while (0)
; #define PG8_LDB(dst, b, h) do { _Pragma("unroll") for (int n = 0; n < 2; ++n) _Pragma("unroll") for (int k = 0; k < 2; ++k) dst[n][k] = *(const LAS bf16x8*)(lds + PG8_SB(b, h) + boff + n * 2048 + k * 1024); } while (0)
; #define PG8_MMA(ai, bj, At, Bt) do { __builtin_amdgcn_s_setprio(1); _Pragma("unroll") for (int m = 0; m < 4; ++m) _Pragma("unroll") for (int n = 0; n < 2; ++n) _Pragma("unroll") for (int k = 0; k < 2; ++k) \
;         acc[ai][bj][m][n] = __builtin_amdgcn_mfma_f32_16x16x32_bf16(Bt[n][k], At[m][k], acc[ai][bj][m][n], 0, 0, 0); __builtin_amdgcn_s_setprio(0); } while (0)
; #define PG8_WAIT_V(n) asm volatile("s_waitcnt vmcnt(" #n ")" ::: "memory")
; #define PG8_WAIT_L(n) asm volatile("s_waitcnt lgkmcnt(" #n ")" ::: "memory")
; #define PG8_BAR __builtin_amdgcn_s_barrier()
; #define PG8_SCHED __builtin_amdgcn_sched_barrier(0)
; template <class Epi, class Sched>
; __device__ __forceinline__ void gemm_phase(LAS unsigned char* lds, const int lda, const int ldb, const int K, const Sched& S, const Epi& E, int tid) {
;     ...
;         for (int t = 0; t < nt; t += 2) {
;             const bool last = (t == nt - 2);
;             const char* a1 = cA + (size_t)(t + 1) * kstep;
;             const char* a2 = last ? nA : cA + (size_t)(t + 2) * kstep; const char* b2 = last ? nB : cB + (size_t)(t + 2) * kstep;
;             const char* a3 = a2 + kstep; const char* b3 = b2 + kstep;
;             PG8_LDB(B0, 0, 0); PG8_LDB(B1, 0, 1); PG8_SCHED; PG8_LDA(At, 0, 0); PG8_STAGE(PG8_SA(1, 1), a1 + hA, voffA);
;             PG8_WAIT_V(8); PG8_WAIT_L(0); PG8_BAR; PG8_MMA(0, 0, At, B0); PG8_MMA(0, 1, At, B1); PG8_BAR; PG8_SCHED;
;             PG8_LDA(At, 0, 1); PG8_STAGE(PG8_SB(0, 0), b2, voffB); PG8_STAGE(PG8_SB(0, 1), b2 + hB, voffB); PG8_STAGE(PG8_SA(0, 0), a2, voffA);
;             PG8_WAIT_V(8); PG8_WAIT_L(0); PG8_BAR; PG8_MMA(1, 0, At, B0); PG8_MMA(1, 1, At, B1); PG8_BAR; PG8_SCHED;
.LBB0_262:
	s_add_u32 s10, s8, 0xfff80080
	s_addc_u32 s11, s9, -1
	s_add_i32 s34, 0, 0x10000
	s_cmp_eq_u32 s43, 28
	s_cselect_b32 s15, s5, s11
	s_cselect_b32 s14, s4, s10
	s_cselect_b32 s11, s7, s42
	s_cselect_b32 s10, s6, s33
	s_add_i32 s35, 0, 0x14000
	v_add_u32_e32 v160, s34, v145
	v_add_u32_e32 v176, s35, v145
	ds_read_b128 v[148:151], v160
	ds_read_b128 v[152:155], v160 offset:1024
	ds_read_b128 v[156:159], v160 offset:2048
	ds_read_b128 v[160:163], v160 offset:3072
	ds_read_b128 v[164:167], v176
	ds_read_b128 v[168:171], v176 offset:1024
	ds_read_b128 v[172:175], v176 offset:2048
	ds_read_b128 v[176:179], v176 offset:3072
	s_add_i32 m0, s17, 0xc000
	ds_read_b128 v[180:183], v147
	ds_read_b128 v[184:187], v147 offset:1024
	ds_read_b128 v[188:191], v147 offset:2048
	ds_read_b128 v[192:195], v147 offset:3072
	ds_read_b128 v[200:203], v147 offset:4096
	ds_read_b128 v[204:207], v147 offset:5120
	ds_read_b128 v[208:211], v147 offset:6144
	ds_read_b128 v[212:215], v147 offset:7168
	global_load_lds_dwordx4 v140, s[8:9]
	s_add_i32 m0, s17, 0xe000
	s_nop 0
	global_load_lds_dwordx4 v142, s[8:9]
	s_waitcnt vmcnt(8) lgkmcnt(0)
	s_barrier
	s_setprio 1
	v_mfma_f32_16x16x32_bf16 v[126:129], v[148:151], v[180:183], v[126:129]
	v_mfma_f32_16x16x32_bf16 v[122:125], v[156:159], v[180:183], v[122:125]
	v_mfma_f32_16x16x32_bf16 v[118:121], v[148:151], v[188:191], v[118:121]
	v_mfma_f32_16x16x32_bf16 v[114:117], v[156:159], v[188:191], v[114:117]
	v_mfma_f32_16x16x32_bf16 v[110:113], v[148:151], v[200:203], v[110:113]
	v_mfma_f32_16x16x32_bf16 v[102:105], v[156:159], v[200:203], v[102:105]
	v_mfma_f32_16x16x32_bf16 v[94:97], v[148:151], v[208:211], v[94:97]
	v_mfma_f32_16x16x32_bf16 v[86:89], v[156:159], v[208:211], v[86:89]
	v_mfma_f32_16x16x32_bf16 v[126:129], v[152:155], v[184:187], v[126:129]
	v_mfma_f32_16x16x32_bf16 v[122:125], v[160:163], v[184:187], v[122:125]
	v_mfma_f32_16x16x32_bf16 v[118:121], v[152:155], v[192:195], v[118:121]
	v_mfma_f32_16x16x32_bf16 v[114:117], v[160:163], v[192:195], v[114:117]
	v_mfma_f32_16x16x32_bf16 v[110:113], v[152:155], v[204:207], v[110:113]
	v_mfma_f32_16x16x32_bf16 v[102:105], v[160:163], v[204:207], v[102:105]
	v_mfma_f32_16x16x32_bf16 v[94:97], v[152:155], v[212:215], v[94:97]
	v_mfma_f32_16x16x32_bf16 v[86:89], v[160:163], v[212:215], v[86:89]
	s_setprio 0
	s_setprio 1
	v_mfma_f32_16x16x32_bf16 v[106:109], v[164:167], v[180:183], v[106:109]
	v_mfma_f32_16x16x32_bf16 v[98:101], v[172:175], v[180:183], v[98:101]
	v_mfma_f32_16x16x32_bf16 v[90:93], v[164:167], v[188:191], v[90:93]
	v_mfma_f32_16x16x32_bf16 v[82:85], v[172:175], v[188:191], v[82:85]
	v_mfma_f32_16x16x32_bf16 v[78:81], v[164:167], v[200:203], v[78:81]
	v_mfma_f32_16x16x32_bf16 v[74:77], v[172:175], v[200:203], v[74:77]
	v_mfma_f32_16x16x32_bf16 v[70:73], v[164:167], v[208:211], v[70:73]
	v_mfma_f32_16x16x32_bf16 v[66:69], v[172:175], v[208:211], v[66:69]
	v_mfma_f32_16x16x32_bf16 v[106:109], v[168:171], v[184:187], v[106:109]
	v_mfma_f32_16x16x32_bf16 v[98:101], v[176:179], v[184:187], v[98:101]
	v_mfma_f32_16x16x32_bf16 v[90:93], v[168:171], v[192:195], v[90:93]
	v_mfma_f32_16x16x32_bf16 v[82:85], v[176:179], v[192:195], v[82:85]
	v_mfma_f32_16x16x32_bf16 v[78:81], v[168:171], v[204:207], v[78:81]
	v_mfma_f32_16x16x32_bf16 v[74:77], v[176:179], v[204:207], v[74:77]
	v_mfma_f32_16x16x32_bf16 v[70:73], v[168:171], v[212:215], v[70:73]
	v_mfma_f32_16x16x32_bf16 v[66:69], v[176:179], v[212:215], v[66:69]
	s_setprio 0
	s_barrier
	s_add_u32 s98, s10, s30
	s_addc_u32 s99, s11, s31
	s_add_u32 s100, s14, s30
	s_addc_u32 s101, s15, s31
	s_add_i32 s34, s34, s16
	s_mov_b32 m0, s34
	ds_read_b128 v[180:183], v147 offset:16384
	ds_read_b128 v[184:187], v147 offset:17408
	ds_read_b128 v[188:191], v147 offset:18432
	ds_read_b128 v[192:195], v147 offset:19456
	ds_read_b128 v[200:203], v147 offset:20480
	ds_read_b128 v[204:207], v147 offset:21504
	ds_read_b128 v[208:211], v147 offset:22528
	ds_read_b128 v[212:215], v147 offset:23552
	global_load_lds_dwordx4 v132, s[10:11]
	s_add_i32 m0, s34, 0x2000
	s_add_u32 s44, s10, 0x80000
	s_addc_u32 s45, s11, 0
	s_add_i32 s34, s35, s16
	global_load_lds_dwordx4 v136, s[10:11]
	s_mov_b32 m0, s34
	s_nop 0
	global_load_lds_dwordx4 v132, s[44:45]
	s_add_i32 m0, s34, 0x2000
	s_nop 0
	global_load_lds_dwordx4 v136, s[44:45]
	s_mov_b32 m0, s17
	s_nop 0
	global_load_lds_dwordx4 v130, s[14:15]
	s_mov_b32 m0, s18
	s_nop 0
	global_load_lds_dwordx4 v134, s[14:15]
	s_waitcnt vmcnt(8) lgkmcnt(0)
	s_barrier
	s_setprio 1
	v_mfma_f32_16x16x32_bf16 v[62:65], v[148:151], v[180:183], v[62:65]
	v_mfma_f32_16x16x32_bf16 v[58:61], v[156:159], v[180:183], v[58:61]
	v_mfma_f32_16x16x32_bf16 v[54:57], v[148:151], v[188:191], v[54:57]
	v_mfma_f32_16x16x32_bf16 v[50:53], v[156:159], v[188:191], v[50:53]
	v_mfma_f32_16x16x32_bf16 v[46:49], v[148:151], v[200:203], v[46:49]
	v_mfma_f32_16x16x32_bf16 v[38:41], v[156:159], v[200:203], v[38:41]
	v_mfma_f32_16x16x32_bf16 v[30:33], v[148:151], v[208:211], v[30:33]
	v_mfma_f32_16x16x32_bf16 v[22:25], v[156:159], v[208:211], v[22:25]
	v_mfma_f32_16x16x32_bf16 v[62:65], v[152:155], v[184:187], v[62:65]
	v_mfma_f32_16x16x32_bf16 v[58:61], v[160:163], v[184:187], v[58:61]
	v_mfma_f32_16x16x32_bf16 v[54:57], v[152:155], v[192:195], v[54:57]
	v_mfma_f32_16x16x32_bf16 v[50:53], v[160:163], v[192:195], v[50:53]
	v_mfma_f32_16x16x32_bf16 v[46:49], v[152:155], v[204:207], v[46:49]
	v_mfma_f32_16x16x32_bf16 v[38:41], v[160:163], v[204:207], v[38:41]
	v_mfma_f32_16x16x32_bf16 v[30:33], v[152:155], v[212:215], v[30:33]
	v_mfma_f32_16x16x32_bf16 v[22:25], v[160:163], v[212:215], v[22:25]
	s_setprio 0
	s_setprio 1
	v_mfma_f32_16x16x32_bf16 v[42:45], v[164:167], v[180:183], v[42:45]
	v_mfma_f32_16x16x32_bf16 v[34:37], v[172:175], v[180:183], v[34:37]
	v_mfma_f32_16x16x32_bf16 v[26:29], v[164:167], v[188:191], v[26:29]
	v_mfma_f32_16x16x32_bf16 v[18:21], v[172:175], v[188:191], v[18:21]
	v_mfma_f32_16x16x32_bf16 v[14:17], v[164:167], v[200:203], v[14:17]
	v_mfma_f32_16x16x32_bf16 v[10:13], v[172:175], v[200:203], v[10:13]
	v_mfma_f32_16x16x32_bf16 v[6:9], v[164:167], v[208:211], v[6:9]
	v_mfma_f32_16x16x32_bf16 v[2:5], v[172:175], v[208:211], v[2:5]
	v_mfma_f32_16x16x32_bf16 v[42:45], v[168:171], v[184:187], v[42:45]
	v_mfma_f32_16x16x32_bf16 v[34:37], v[176:179], v[184:187], v[34:37]
	v_mfma_f32_16x16x32_bf16 v[26:29], v[168:171], v[192:195], v[26:29]
	v_mfma_f32_16x16x32_bf16 v[18:21], v[176:179], v[192:195], v[18:21]
	v_mfma_f32_16x16x32_bf16 v[14:17], v[168:171], v[204:207], v[14:17]
	v_mfma_f32_16x16x32_bf16 v[10:13], v[176:179], v[204:207], v[10:13]
	v_mfma_f32_16x16x32_bf16 v[6:9], v[168:171], v[212:215], v[6:9]
	v_mfma_f32_16x16x32_bf16 v[2:5], v[176:179], v[212:215], v[2:5]
	s_setprio 0
	s_barrier
; #define PG8_STAGE(bufoff, gbase, voff) do { _Pragma("unroll") for (int _i = 0; _i < 2; ++_i) \
;         __builtin_amdgcn_global_load_lds((const unsigned*)((const char*)(gbase) + (voff)[_i]), (LAS unsigned*)(lds + (bufoff) + ldsw + _i * 8192), 16, 0, 0); } while (0)
; #define PG8_LDA(dst, b, h) do { _Pragma("unroll") for (int m = 0; m < 4; ++m) _Pragma("unroll") for (int k = 0; k < 2; ++k) dst[m][k] = *(const LAS bf16x8*)(lds + PG8_SA(b, h) + aoff + m * 2048 + k * 1024); } while (0)
; #define PG8_LDB(dst, b, h) do { _Pragma("unroll") for (int n = 0; n < 2; ++n) _Pragma("unroll") for (int k = 0; k < 2; ++k) dst[n][k] = *(const LAS bf16x8*)(lds + PG8_SB(b, h) + boff + n * 2048 + k * 1024); } while (0)
; #define PG8_MMA(ai, bj, At, Bt) do { __builtin_amdgcn_s_setprio(1); _Pragma("unroll") for (int m = 0; m < 4; ++m) _Pragma("unroll") for (int n = 0; n < 2; ++n) _Pragma("unroll") for (int k = 0; k < 2; ++k) \
;         acc[ai][bj][m][n] = __builtin_amdgcn_mfma_f32_16x16x32_bf16(Bt[n][k], At[m][k], acc[ai][bj][m][n], 0, 0, 0); __builtin_amdgcn_s_setprio(0); } while (0)
; #define PG8_WAIT_V(n) asm volatile("s_waitcnt vmcnt(" #n ")" ::: "memory")
; #define PG8_WAIT_L(n) asm volatile("s_waitcnt lgkmcnt(" #n ")" ::: "memory")
; #define PG8_BAR __builtin_amdgcn_s_barrier()
; #define PG8_SCHED __builtin_amdgcn_sched_barrier(0)
; template <class Epi, class Sched>
; __device__ __forceinline__ void gemm_phase(LAS unsigned char* lds, const int lda, const int ldb, const int K, const Sched& S, const Epi& E, int tid) {
;     ...
;             PG8_LDB(B0, 1, 0); PG8_LDB(B1, 1, 1); PG8_SCHED; PG8_LDA(At, 1, 0); PG8_STAGE(PG8_SA(0, 1), a2 + hA, voffA);
;             PG8_WAIT_V(8); PG8_WAIT_L(0); PG8_BAR; PG8_MMA(0, 0, At, B0); PG8_MMA(0, 1, At, B1); PG8_BAR; PG8_SCHED;
;             PG8_LDA(At, 1, 1); PG8_STAGE(PG8_SB(1, 0), b3, voffB); PG8_STAGE(PG8_SB(1, 1), b3 + hB, voffB); PG8_STAGE(PG8_SA(1, 0), a3, voffA);
;             PG8_WAIT_V(8); PG8_WAIT_L(0); PG8_BAR; PG8_MMA(1, 0, At, B0); PG8_MMA(1, 1, At, B1); PG8_BAR; PG8_SCHED;
;         }
;         if (wr == 0) PG8_BAR;
	s_add_i32 s34, 0, 0x18000
	s_add_i32 s35, 0, 0x1c000
	v_add_u32_e32 v160, s34, v145
	v_add_u32_e32 v176, s35, v145
	ds_read_b128 v[148:151], v160
	ds_read_b128 v[152:155], v160 offset:1024
	ds_read_b128 v[156:159], v160 offset:2048
	ds_read_b128 v[160:163], v160 offset:3072
	ds_read_b128 v[164:167], v176
	ds_read_b128 v[168:171], v176 offset:1024
	ds_read_b128 v[172:175], v176 offset:2048
	ds_read_b128 v[176:179], v176 offset:3072
	s_add_u32 s14, s14, 0x80000
	s_addc_u32 s15, s15, 0
	s_mov_b32 m0, s19
	ds_read_b128 v[180:183], v147 offset:32768
	ds_read_b128 v[184:187], v147 offset:33792
	ds_read_b128 v[188:191], v147 offset:34816
	ds_read_b128 v[192:195], v147 offset:35840
	ds_read_b128 v[200:203], v147 offset:36864
	ds_read_b128 v[204:207], v147 offset:37888
	ds_read_b128 v[208:211], v147 offset:38912
	ds_read_b128 v[212:215], v147 offset:39936
	global_load_lds_dwordx4 v130, s[14:15]
	s_mov_b32 m0, s20
	s_nop 0
	global_load_lds_dwordx4 v134, s[14:15]
	s_waitcnt vmcnt(8) lgkmcnt(0)
	s_barrier
	s_setprio 1
	v_mfma_f32_16x16x32_bf16 v[126:129], v[148:151], v[180:183], v[126:129]
	v_mfma_f32_16x16x32_bf16 v[122:125], v[156:159], v[180:183], v[122:125]
	v_mfma_f32_16x16x32_bf16 v[118:121], v[148:151], v[188:191], v[118:121]
	v_mfma_f32_16x16x32_bf16 v[114:117], v[156:159], v[188:191], v[114:117]
	v_mfma_f32_16x16x32_bf16 v[110:113], v[148:151], v[200:203], v[110:113]
	v_mfma_f32_16x16x32_bf16 v[102:105], v[156:159], v[200:203], v[102:105]
	v_mfma_f32_16x16x32_bf16 v[94:97], v[148:151], v[208:211], v[94:97]
	v_mfma_f32_16x16x32_bf16 v[86:89], v[156:159], v[208:211], v[86:89]
	v_mfma_f32_16x16x32_bf16 v[126:129], v[152:155], v[184:187], v[126:129]
	v_mfma_f32_16x16x32_bf16 v[122:125], v[160:163], v[184:187], v[122:125]
	v_mfma_f32_16x16x32_bf16 v[118:121], v[152:155], v[192:195], v[118:121]
	v_mfma_f32_16x16x32_bf16 v[114:117], v[160:163], v[192:195], v[114:117]
	v_mfma_f32_16x16x32_bf16 v[110:113], v[152:155], v[204:207], v[110:113]
	v_mfma_f32_16x16x32_bf16 v[102:105], v[160:163], v[204:207], v[102:105]
	v_mfma_f32_16x16x32_bf16 v[94:97], v[152:155], v[212:215], v[94:97]
	v_mfma_f32_16x16x32_bf16 v[86:89], v[160:163], v[212:215], v[86:89]
	s_setprio 0
	s_setprio 1
	v_mfma_f32_16x16x32_bf16 v[106:109], v[164:167], v[180:183], v[106:109]
	v_mfma_f32_16x16x32_bf16 v[98:101], v[172:175], v[180:183], v[98:101]
	v_mfma_f32_16x16x32_bf16 v[90:93], v[164:167], v[188:191], v[90:93]
	v_mfma_f32_16x16x32_bf16 v[82:85], v[172:175], v[188:191], v[82:85]
	v_mfma_f32_16x16x32_bf16 v[78:81], v[164:167], v[200:203], v[78:81]
	v_mfma_f32_16x16x32_bf16 v[74:77], v[172:175], v[200:203], v[74:77]
	v_mfma_f32_16x16x32_bf16 v[70:73], v[164:167], v[208:211], v[70:73]
	v_mfma_f32_16x16x32_bf16 v[66:69], v[172:175], v[208:211], v[66:69]
	v_mfma_f32_16x16x32_bf16 v[106:109], v[168:171], v[184:187], v[106:109]
	v_mfma_f32_16x16x32_bf16 v[98:101], v[176:179], v[184:187], v[98:101]
	v_mfma_f32_16x16x32_bf16 v[90:93], v[168:171], v[192:195], v[90:93]
	v_mfma_f32_16x16x32_bf16 v[82:85], v[176:179], v[192:195], v[82:85]
	v_mfma_f32_16x16x32_bf16 v[78:81], v[168:171], v[204:207], v[78:81]
	v_mfma_f32_16x16x32_bf16 v[74:77], v[176:179], v[204:207], v[74:77]
	v_mfma_f32_16x16x32_bf16 v[70:73], v[168:171], v[212:215], v[70:73]
	v_mfma_f32_16x16x32_bf16 v[66:69], v[176:179], v[212:215], v[66:69]
	s_setprio 0
	s_barrier
	s_add_i32 s14, s34, s16
	s_mov_b32 m0, s14
	ds_read_b128 v[180:183], v147 offset:49152
	ds_read_b128 v[184:187], v147 offset:50176
	ds_read_b128 v[188:191], v147 offset:51200
	ds_read_b128 v[192:195], v147 offset:52224
	ds_read_b128 v[200:203], v147 offset:53248
	ds_read_b128 v[204:207], v147 offset:54272
	ds_read_b128 v[208:211], v147 offset:55296
	ds_read_b128 v[212:215], v147 offset:56320
	global_load_lds_dwordx4 v132, s[98:99]
	s_add_i32 m0, s14, 0x2000
	s_add_u32 s10, s10, 0x80080
	s_addc_u32 s11, s11, 0
	s_add_i32 s14, s35, s16
	global_load_lds_dwordx4 v136, s[98:99]
	s_mov_b32 m0, s14
	s_nop 0
	global_load_lds_dwordx4 v132, s[10:11]
	s_add_i32 m0, s14, 0x2000
	s_nop 0
	global_load_lds_dwordx4 v136, s[10:11]
	s_mov_b32 m0, s21
	s_nop 0
	global_load_lds_dwordx4 v130, s[100:101]
	s_mov_b32 m0, s22
	s_nop 0
	global_load_lds_dwordx4 v134, s[100:101]
	s_waitcnt vmcnt(8) lgkmcnt(0)
	s_barrier
	s_setprio 1
	v_mfma_f32_16x16x32_bf16 v[62:65], v[148:151], v[180:183], v[62:65]
	v_mfma_f32_16x16x32_bf16 v[58:61], v[156:159], v[180:183], v[58:61]
	v_mfma_f32_16x16x32_bf16 v[54:57], v[148:151], v[188:191], v[54:57]
	v_mfma_f32_16x16x32_bf16 v[50:53], v[156:159], v[188:191], v[50:53]
	v_mfma_f32_16x16x32_bf16 v[46:49], v[148:151], v[200:203], v[46:49]
	v_mfma_f32_16x16x32_bf16 v[38:41], v[156:159], v[200:203], v[38:41]
	v_mfma_f32_16x16x32_bf16 v[30:33], v[148:151], v[208:211], v[30:33]
	v_mfma_f32_16x16x32_bf16 v[22:25], v[156:159], v[208:211], v[22:25]
	v_mfma_f32_16x16x32_bf16 v[62:65], v[152:155], v[184:187], v[62:65]
	v_mfma_f32_16x16x32_bf16 v[58:61], v[160:163], v[184:187], v[58:61]
	v_mfma_f32_16x16x32_bf16 v[54:57], v[152:155], v[192:195], v[54:57]
	v_mfma_f32_16x16x32_bf16 v[50:53], v[160:163], v[192:195], v[50:53]
	v_mfma_f32_16x16x32_bf16 v[46:49], v[152:155], v[204:207], v[46:49]
	v_mfma_f32_16x16x32_bf16 v[38:41], v[160:163], v[204:207], v[38:41]
	v_mfma_f32_16x16x32_bf16 v[30:33], v[152:155], v[212:215], v[30:33]
	v_mfma_f32_16x16x32_bf16 v[22:25], v[160:163], v[212:215], v[22:25]
	s_setprio 0
	s_setprio 1
	v_mfma_f32_16x16x32_bf16 v[42:45], v[164:167], v[180:183], v[42:45]
	v_mfma_f32_16x16x32_bf16 v[34:37], v[172:175], v[180:183], v[34:37]
	v_mfma_f32_16x16x32_bf16 v[26:29], v[164:167], v[188:191], v[26:29]
	v_mfma_f32_16x16x32_bf16 v[18:21], v[172:175], v[188:191], v[18:21]
	v_mfma_f32_16x16x32_bf16 v[14:17], v[164:167], v[200:203], v[14:17]
	v_mfma_f32_16x16x32_bf16 v[10:13], v[172:175], v[200:203], v[10:13]
	v_mfma_f32_16x16x32_bf16 v[6:9], v[164:167], v[208:211], v[6:9]
	v_mfma_f32_16x16x32_bf16 v[2:5], v[172:175], v[208:211], v[2:5]
	v_mfma_f32_16x16x32_bf16 v[42:45], v[168:171], v[184:187], v[42:45]
	v_mfma_f32_16x16x32_bf16 v[34:37], v[176:179], v[184:187], v[34:37]
	v_mfma_f32_16x16x32_bf16 v[26:29], v[168:171], v[192:195], v[26:29]
	v_mfma_f32_16x16x32_bf16 v[18:21], v[176:179], v[192:195], v[18:21]
	v_mfma_f32_16x16x32_bf16 v[14:17], v[168:171], v[204:207], v[14:17]
	v_mfma_f32_16x16x32_bf16 v[10:13], v[176:179], v[204:207], v[10:13]
	v_mfma_f32_16x16x32_bf16 v[6:9], v[168:171], v[212:215], v[6:9]
	v_mfma_f32_16x16x32_bf16 v[2:5], v[176:179], v[212:215], v[2:5]
	s_setprio 0
	s_barrier
	s_add_i32 s43, s43, 2
	s_add_u32 s8, s8, 0x100
	s_addc_u32 s9, s9, 0
	s_add_u32 s33, s33, 0x100
	s_addc_u32 s42, s42, 0
	s_cmp_gt_u32 s43, 29
	s_cbranch_scc0 .LBB0_262
	s_and_b64 vcc, exec, s[2:3]
	s_cbranch_vccz .LBB0_265
	s_barrier

; #define PG8_STAGE(bufoff, gbase, voff) do { _Pragma("unroll") for (int _i = 0; _i < 2; ++_i) \
;         __builtin_amdgcn_global_load_lds((const unsigned*)((const char*)(gbase) + (voff)[_i]), (LAS unsigned*)(lds + (bufoff) + ldsw + _i * 8192), 16, 0, 0); } while (0)
; #define PG8_LDA(dst, b, h) do { _Pragma("unroll") for (int m = 0; m < 4; ++m) _Pragma("unroll") for (int k = 0; k < 2; ++k) dst[m][k] = *(const LAS bf16x8*)(lds + PG8_SA(b, h) + aoff + m * 2048 + k * 1024); } while (0)
; #define PG8_LDB(dst, b, h) do { _Pragma("unroll") for (int n = 0; n < 2; ++n) _Pragma("unroll") for (int k = 0; k < 2; ++k) dst[n][k] = *(const LAS bf16x8*)(lds + PG8_SB(b, h) + boff + n * 2048 + k * 1024); } while (0)
; #define PG8_MMA(ai, bj, At, Bt) do { __builtin_amdgcn_s_setprio(1); _Pragma("unroll") for (int m = 0; m < 4; ++m) _Pragma("unroll") for (int n = 0; n < 2; ++n) _Pragma("unroll") for (int k = 0; k < 2; ++k) \
;         acc[ai][bj][m][n] = __builtin_amdgcn_mfma_f32_16x16x32_bf16(Bt[n][k], At[m][k], acc[ai][bj][m][n], 0, 0, 0); __builtin_amdgcn_s_setprio(0); } while (0)
; #define PG8_WAIT_V(n) asm volatile("s_waitcnt vmcnt(" #n ")" ::: "memory")
; #define PG8_WAIT_L(n) asm volatile("s_waitcnt lgkmcnt(" #n ")" ::: "memory")
; #define PG8_BAR __builtin_amdgcn_s_barrier()
; #define PG8_SCHED __builtin_amdgcn_sched_barrier(0)
; template <class Epi, class Sched>
; __device__ __forceinline__ void gemm_phase(LAS unsigned char* lds, const int lda, const int ldb, const int K, const Sched& S, const Epi& E, int tid) {
;     ...
;         for (int t = 0; t < nt; t += 2) {
;             const bool last = (t == nt - 2);
;             const char* a1 = cA + (size_t)(t + 1) * kstep;
;             const char* a2 = last ? nA : cA + (size_t)(t + 2) * kstep; const char* b2 = last ? nB : cB + (size_t)(t + 2) * kstep;
;             const char* a3 = a2 + kstep; const char* b3 = b2 + kstep;
;             PG8_LDB(B0, 0, 0); PG8_LDB(B1, 0, 1); PG8_SCHED; PG8_LDA(At, 0, 0); PG8_STAGE(PG8_SA(1, 1), a1 + hA, voffA);
;             PG8_WAIT_V(8); PG8_WAIT_L(0); PG8_BAR; PG8_MMA(0, 0, At, B0); PG8_MMA(0, 1, At, B1); PG8_BAR; PG8_SCHED;
;             PG8_LDA(At, 0, 1); PG8_STAGE(PG8_SB(0, 0), b2, voffB); PG8_STAGE(PG8_SB(0, 1), b2 + hB, voffB); PG8_STAGE(PG8_SA(0, 0), a2, voffA);
;             PG8_WAIT_V(8); PG8_WAIT_L(0); PG8_BAR; PG8_MMA(1, 0, At, B0); PG8_MMA(1, 1, At, B1); PG8_BAR; PG8_SCHED;
.LBB0_290:
	s_add_u32 s14, s10, 0xfff80080
	s_addc_u32 s15, s11, -1
	s_add_i32 s34, 0, 0x10000
	s_cmp_eq_u32 s42, 28
	s_cselect_b32 s17, s5, s15
	s_cselect_b32 s16, s4, s14
	s_cselect_b32 s15, s7, s33
	s_cselect_b32 s14, s6, s18
	s_add_i32 s35, 0, 0x14000
	v_add_u32_e32 v156, s34, v163
	v_add_u32_e32 v160, s35, v163
	ds_read_b128 v[144:147], v156
	ds_read_b128 v[148:151], v156 offset:1024
	ds_read_b128 v[152:155], v156 offset:2048
	ds_read_b128 v[156:159], v156 offset:3072
	ds_read_b128 v[166:169], v160
	ds_read_b128 v[170:173], v160 offset:1024
	ds_read_b128 v[174:177], v160 offset:2048
	ds_read_b128 v[178:181], v160 offset:3072
	s_add_i32 m0, s21, 0xc000
	ds_read_b128 v[182:185], v164
	ds_read_b128 v[186:189], v164 offset:1024
	ds_read_b128 v[190:193], v164 offset:2048
	ds_read_b128 v[194:197], v164 offset:3072
	ds_read_b128 v[200:203], v164 offset:4096
	ds_read_b128 v[204:207], v164 offset:5120
	ds_read_b128 v[208:211], v164 offset:6144
	ds_read_b128 v[212:215], v164 offset:7168
	global_load_lds_dwordx4 v140, s[10:11]
	s_add_i32 m0, s21, 0xe000
	s_nop 0
	global_load_lds_dwordx4 v142, s[10:11]
	s_waitcnt vmcnt(8) lgkmcnt(0)
	s_barrier
	s_setprio 1
	v_mfma_f32_16x16x32_bf16 v[126:129], v[144:147], v[182:185], v[126:129]
	v_mfma_f32_16x16x32_bf16 v[122:125], v[152:155], v[182:185], v[122:125]
	v_mfma_f32_16x16x32_bf16 v[118:121], v[144:147], v[190:193], v[118:121]
	v_mfma_f32_16x16x32_bf16 v[114:117], v[152:155], v[190:193], v[114:117]
	v_mfma_f32_16x16x32_bf16 v[102:105], v[144:147], v[200:203], v[102:105]
	v_mfma_f32_16x16x32_bf16 v[98:101], v[152:155], v[200:203], v[98:101]
	v_mfma_f32_16x16x32_bf16 v[86:89], v[144:147], v[208:211], v[86:89]
	v_mfma_f32_16x16x32_bf16 v[82:85], v[152:155], v[208:211], v[82:85]
	v_mfma_f32_16x16x32_bf16 v[126:129], v[148:151], v[186:189], v[126:129]
	v_mfma_f32_16x16x32_bf16 v[122:125], v[156:159], v[186:189], v[122:125]
	v_mfma_f32_16x16x32_bf16 v[118:121], v[148:151], v[194:197], v[118:121]
	v_mfma_f32_16x16x32_bf16 v[114:117], v[156:159], v[194:197], v[114:117]
	v_mfma_f32_16x16x32_bf16 v[102:105], v[148:151], v[204:207], v[102:105]
	v_mfma_f32_16x16x32_bf16 v[98:101], v[156:159], v[204:207], v[98:101]
	v_mfma_f32_16x16x32_bf16 v[86:89], v[148:151], v[212:215], v[86:89]
	v_mfma_f32_16x16x32_bf16 v[82:85], v[156:159], v[212:215], v[82:85]
	s_setprio 0
	s_setprio 1
	v_mfma_f32_16x16x32_bf16 v[110:113], v[166:169], v[182:185], v[110:113]
	v_mfma_f32_16x16x32_bf16 v[106:109], v[174:177], v[182:185], v[106:109]
	v_mfma_f32_16x16x32_bf16 v[94:97], v[166:169], v[190:193], v[94:97]
	v_mfma_f32_16x16x32_bf16 v[90:93], v[174:177], v[190:193], v[90:93]
	v_mfma_f32_16x16x32_bf16 v[78:81], v[166:169], v[200:203], v[78:81]
	v_mfma_f32_16x16x32_bf16 v[74:77], v[174:177], v[200:203], v[74:77]
	v_mfma_f32_16x16x32_bf16 v[70:73], v[166:169], v[208:211], v[70:73]
	v_mfma_f32_16x16x32_bf16 v[66:69], v[174:177], v[208:211], v[66:69]
	v_mfma_f32_16x16x32_bf16 v[110:113], v[170:173], v[186:189], v[110:113]
	v_mfma_f32_16x16x32_bf16 v[106:109], v[178:181], v[186:189], v[106:109]
	v_mfma_f32_16x16x32_bf16 v[94:97], v[170:173], v[194:197], v[94:97]
	v_mfma_f32_16x16x32_bf16 v[90:93], v[178:181], v[194:197], v[90:93]
	v_mfma_f32_16x16x32_bf16 v[78:81], v[170:173], v[204:207], v[78:81]
	v_mfma_f32_16x16x32_bf16 v[74:77], v[178:181], v[204:207], v[74:77]
	v_mfma_f32_16x16x32_bf16 v[70:73], v[170:173], v[212:215], v[70:73]
	v_mfma_f32_16x16x32_bf16 v[66:69], v[178:181], v[212:215], v[66:69]
	s_setprio 0
	s_barrier
	s_add_u32 s98, s14, s30
	s_addc_u32 s99, s15, s31
	s_add_u32 s100, s16, s30
	s_addc_u32 s101, s17, s31
	s_add_i32 s34, s34, s20
	s_mov_b32 m0, s34
	ds_read_b128 v[182:185], v164 offset:16384
	ds_read_b128 v[186:189], v164 offset:17408
	ds_read_b128 v[190:193], v164 offset:18432
	ds_read_b128 v[194:197], v164 offset:19456
	ds_read_b128 v[200:203], v164 offset:20480
	ds_read_b128 v[204:207], v164 offset:21504
	ds_read_b128 v[208:211], v164 offset:22528
	ds_read_b128 v[212:215], v164 offset:23552
	global_load_lds_dwordx4 v0, s[14:15]
	s_add_i32 m0, s34, 0x2000
	s_add_u32 s44, s14, 0x80000
	s_addc_u32 s45, s15, 0
	s_add_i32 s34, s35, s20
	global_load_lds_dwordx4 v134, s[14:15]
	s_mov_b32 m0, s34
	s_nop 0
	global_load_lds_dwordx4 v0, s[44:45]
	s_add_i32 m0, s34, 0x2000
	s_nop 0
	global_load_lds_dwordx4 v134, s[44:45]
	s_mov_b32 m0, s21
	s_nop 0
	global_load_lds_dwordx4 v130, s[16:17]
	s_mov_b32 m0, s22
	s_nop 0
	global_load_lds_dwordx4 v132, s[16:17]
	s_waitcnt vmcnt(8) lgkmcnt(0)
	s_barrier
	s_setprio 1
	v_mfma_f32_16x16x32_bf16 v[62:65], v[144:147], v[182:185], v[62:65]
	v_mfma_f32_16x16x32_bf16 v[58:61], v[152:155], v[182:185], v[58:61]
	v_mfma_f32_16x16x32_bf16 v[54:57], v[144:147], v[190:193], v[54:57]
	v_mfma_f32_16x16x32_bf16 v[50:53], v[152:155], v[190:193], v[50:53]
	v_mfma_f32_16x16x32_bf16 v[38:41], v[144:147], v[200:203], v[38:41]
	v_mfma_f32_16x16x32_bf16 v[34:37], v[152:155], v[200:203], v[34:37]
	v_mfma_f32_16x16x32_bf16 v[22:25], v[144:147], v[208:211], v[22:25]
	v_mfma_f32_16x16x32_bf16 v[18:21], v[152:155], v[208:211], v[18:21]
	v_mfma_f32_16x16x32_bf16 v[62:65], v[148:151], v[186:189], v[62:65]
	v_mfma_f32_16x16x32_bf16 v[58:61], v[156:159], v[186:189], v[58:61]
	v_mfma_f32_16x16x32_bf16 v[54:57], v[148:151], v[194:197], v[54:57]
	v_mfma_f32_16x16x32_bf16 v[50:53], v[156:159], v[194:197], v[50:53]
	v_mfma_f32_16x16x32_bf16 v[38:41], v[148:151], v[204:207], v[38:41]
	v_mfma_f32_16x16x32_bf16 v[34:37], v[156:159], v[204:207], v[34:37]
	v_mfma_f32_16x16x32_bf16 v[22:25], v[148:151], v[212:215], v[22:25]
	v_mfma_f32_16x16x32_bf16 v[18:21], v[156:159], v[212:215], v[18:21]
	s_setprio 0
	s_setprio 1
	v_mfma_f32_16x16x32_bf16 v[46:49], v[166:169], v[182:185], v[46:49]
	v_mfma_f32_16x16x32_bf16 v[42:45], v[174:177], v[182:185], v[42:45]
	v_mfma_f32_16x16x32_bf16 v[30:33], v[166:169], v[190:193], v[30:33]
	v_mfma_f32_16x16x32_bf16 v[26:29], v[174:177], v[190:193], v[26:29]
	v_mfma_f32_16x16x32_bf16 v[14:17], v[166:169], v[200:203], v[14:17]
	v_mfma_f32_16x16x32_bf16 v[10:13], v[174:177], v[200:203], v[10:13]
	v_mfma_f32_16x16x32_bf16 v[6:9], v[166:169], v[208:211], v[6:9]
	v_mfma_f32_16x16x32_bf16 v[2:5], v[174:177], v[208:211], v[2:5]
	v_mfma_f32_16x16x32_bf16 v[46:49], v[170:173], v[186:189], v[46:49]
	v_mfma_f32_16x16x32_bf16 v[42:45], v[178:181], v[186:189], v[42:45]
	v_mfma_f32_16x16x32_bf16 v[30:33], v[170:173], v[194:197], v[30:33]
	v_mfma_f32_16x16x32_bf16 v[26:29], v[178:181], v[194:197], v[26:29]
	v_mfma_f32_16x16x32_bf16 v[14:17], v[170:173], v[204:207], v[14:17]
	v_mfma_f32_16x16x32_bf16 v[10:13], v[178:181], v[204:207], v[10:13]
	v_mfma_f32_16x16x32_bf16 v[6:9], v[170:173], v[212:215], v[6:9]
	v_mfma_f32_16x16x32_bf16 v[2:5], v[178:181], v[212:215], v[2:5]
	s_setprio 0
	s_barrier
; #define PG8_STAGE(bufoff, gbase, voff) do { _Pragma("unroll") for (int _i = 0; _i < 2; ++_i) \
;         __builtin_amdgcn_global_load_lds((const unsigned*)((const char*)(gbase) + (voff)[_i]), (LAS unsigned*)(lds + (bufoff) + ldsw + _i * 8192), 16, 0, 0); } while (0)
; #define PG8_LDA(dst, b, h) do { _Pragma("unroll") for (int m = 0; m < 4; ++m) _Pragma("unroll") for (int k = 0; k < 2; ++k) dst[m][k] = *(const LAS bf16x8*)(lds + PG8_SA(b, h) + aoff + m * 2048 + k * 1024); } while (0)
; #define PG8_LDB(dst, b, h) do { _Pragma("unroll") for (int n = 0; n < 2; ++n) _Pragma("unroll") for (int k = 0; k < 2; ++k) dst[n][k] = *(const LAS bf16x8*)(lds + PG8_SB(b, h) + boff + n * 2048 + k * 1024); } while (0)
; #define PG8_MMA(ai, bj, At, Bt) do { __builtin_amdgcn_s_setprio(1); _Pragma("unroll") for (int m = 0; m < 4; ++m) _Pragma("unroll") for (int n = 0; n < 2; ++n) _Pragma("unroll") for (int k = 0; k < 2; ++k) \
;         acc[ai][bj][m][n] = __builtin_amdgcn_mfma_f32_16x16x32_bf16(Bt[n][k], At[m][k], acc[ai][bj][m][n], 0, 0, 0); __builtin_amdgcn_s_setprio(0); } while (0)
; #define PG8_WAIT_V(n) asm volatile("s_waitcnt vmcnt(" #n ")" ::: "memory")
; #define PG8_WAIT_L(n) asm volatile("s_waitcnt lgkmcnt(" #n ")" ::: "memory")
; #define PG8_BAR __builtin_amdgcn_s_barrier()
; #define PG8_SCHED __builtin_amdgcn_sched_barrier(0)
; template <class Epi, class Sched>
; __device__ __forceinline__ void gemm_phase(LAS unsigned char* lds, const int lda, const int ldb, const int K, const Sched& S, const Epi& E, int tid) {
;     ...
;             PG8_LDB(B0, 1, 0); PG8_LDB(B1, 1, 1); PG8_SCHED; PG8_LDA(At, 1, 0); PG8_STAGE(PG8_SA(0, 1), a2 + hA, voffA);
;             PG8_WAIT_V(8); PG8_WAIT_L(0); PG8_BAR; PG8_MMA(0, 0, At, B0); PG8_MMA(0, 1, At, B1); PG8_BAR; PG8_SCHED;
;             PG8_LDA(At, 1, 1); PG8_STAGE(PG8_SB(1, 0), b3, voffB); PG8_STAGE(PG8_SB(1, 1), b3 + hB, voffB); PG8_STAGE(PG8_SA(1, 0), a3, voffA);
;             PG8_WAIT_V(8); PG8_WAIT_L(0); PG8_BAR; PG8_MMA(1, 0, At, B0); PG8_MMA(1, 1, At, B1); PG8_BAR; PG8_SCHED;
;         }
;         if (wr == 0) PG8_BAR;
	s_add_i32 s34, 0, 0x18000
	s_add_i32 s35, 0, 0x1c000
	v_add_u32_e32 v156, s34, v163
	v_add_u32_e32 v165, s35, v163
	ds_read_b128 v[144:147], v156
	ds_read_b128 v[148:151], v156 offset:1024
	ds_read_b128 v[152:155], v156 offset:2048
	ds_read_b128 v[156:159], v156 offset:3072
	ds_read_b128 v[166:169], v165
	ds_read_b128 v[170:173], v165 offset:1024
	ds_read_b128 v[174:177], v165 offset:2048
	ds_read_b128 v[178:181], v165 offset:3072
	s_add_u32 s16, s16, 0x80000
	s_addc_u32 s17, s17, 0
	s_mov_b32 m0, s23
	ds_read_b128 v[182:185], v164 offset:32768
	ds_read_b128 v[186:189], v164 offset:33792
	ds_read_b128 v[190:193], v164 offset:34816
	ds_read_b128 v[194:197], v164 offset:35840
	ds_read_b128 v[200:203], v164 offset:36864
	ds_read_b128 v[204:207], v164 offset:37888
	ds_read_b128 v[208:211], v164 offset:38912
	ds_read_b128 v[212:215], v164 offset:39936
	global_load_lds_dwordx4 v130, s[16:17]
	s_mov_b32 m0, s25
	s_nop 0
	global_load_lds_dwordx4 v132, s[16:17]
	s_waitcnt vmcnt(8) lgkmcnt(0)
	s_barrier
	s_setprio 1
	v_mfma_f32_16x16x32_bf16 v[126:129], v[144:147], v[182:185], v[126:129]
	v_mfma_f32_16x16x32_bf16 v[122:125], v[152:155], v[182:185], v[122:125]
	v_mfma_f32_16x16x32_bf16 v[118:121], v[144:147], v[190:193], v[118:121]
	v_mfma_f32_16x16x32_bf16 v[114:117], v[152:155], v[190:193], v[114:117]
	v_mfma_f32_16x16x32_bf16 v[102:105], v[144:147], v[200:203], v[102:105]
	v_mfma_f32_16x16x32_bf16 v[98:101], v[152:155], v[200:203], v[98:101]
	v_mfma_f32_16x16x32_bf16 v[86:89], v[144:147], v[208:211], v[86:89]
	v_mfma_f32_16x16x32_bf16 v[82:85], v[152:155], v[208:211], v[82:85]
	v_mfma_f32_16x16x32_bf16 v[126:129], v[148:151], v[186:189], v[126:129]
	v_mfma_f32_16x16x32_bf16 v[122:125], v[156:159], v[186:189], v[122:125]
	v_mfma_f32_16x16x32_bf16 v[118:121], v[148:151], v[194:197], v[118:121]
	v_mfma_f32_16x16x32_bf16 v[114:117], v[156:159], v[194:197], v[114:117]
	v_mfma_f32_16x16x32_bf16 v[102:105], v[148:151], v[204:207], v[102:105]
	v_mfma_f32_16x16x32_bf16 v[98:101], v[156:159], v[204:207], v[98:101]
	v_mfma_f32_16x16x32_bf16 v[86:89], v[148:151], v[212:215], v[86:89]
	v_mfma_f32_16x16x32_bf16 v[82:85], v[156:159], v[212:215], v[82:85]
	s_setprio 0
	s_setprio 1
	v_mfma_f32_16x16x32_bf16 v[110:113], v[166:169], v[182:185], v[110:113]
	v_mfma_f32_16x16x32_bf16 v[106:109], v[174:177], v[182:185], v[106:109]
	v_mfma_f32_16x16x32_bf16 v[94:97], v[166:169], v[190:193], v[94:97]
	v_mfma_f32_16x16x32_bf16 v[90:93], v[174:177], v[190:193], v[90:93]
	v_mfma_f32_16x16x32_bf16 v[78:81], v[166:169], v[200:203], v[78:81]
	v_mfma_f32_16x16x32_bf16 v[74:77], v[174:177], v[200:203], v[74:77]
	v_mfma_f32_16x16x32_bf16 v[70:73], v[166:169], v[208:211], v[70:73]
	v_mfma_f32_16x16x32_bf16 v[66:69], v[174:177], v[208:211], v[66:69]
	v_mfma_f32_16x16x32_bf16 v[110:113], v[170:173], v[186:189], v[110:113]
	v_mfma_f32_16x16x32_bf16 v[106:109], v[178:181], v[186:189], v[106:109]
	v_mfma_f32_16x16x32_bf16 v[94:97], v[170:173], v[194:197], v[94:97]
	v_mfma_f32_16x16x32_bf16 v[90:93], v[178:181], v[194:197], v[90:93]
	v_mfma_f32_16x16x32_bf16 v[78:81], v[170:173], v[204:207], v[78:81]
	v_mfma_f32_16x16x32_bf16 v[74:77], v[178:181], v[204:207], v[74:77]
	v_mfma_f32_16x16x32_bf16 v[70:73], v[170:173], v[212:215], v[70:73]
	v_mfma_f32_16x16x32_bf16 v[66:69], v[178:181], v[212:215], v[66:69]
	s_setprio 0
	s_barrier
	s_add_i32 s16, s34, s20
	s_mov_b32 m0, s16
	ds_read_b128 v[182:185], v164 offset:49152
	ds_read_b128 v[186:189], v164 offset:50176
	ds_read_b128 v[190:193], v164 offset:51200
	ds_read_b128 v[194:197], v164 offset:52224
	ds_read_b128 v[200:203], v164 offset:53248
	ds_read_b128 v[204:207], v164 offset:54272
	ds_read_b128 v[208:211], v164 offset:55296
	ds_read_b128 v[212:215], v164 offset:56320
	global_load_lds_dwordx4 v0, s[98:99]
	s_add_i32 m0, s16, 0x2000
	s_add_u32 s14, s14, 0x80080
	s_addc_u32 s15, s15, 0
	s_add_i32 s16, s35, s20
	global_load_lds_dwordx4 v134, s[98:99]
	s_mov_b32 m0, s16
	s_nop 0
	global_load_lds_dwordx4 v0, s[14:15]
	s_add_i32 m0, s16, 0x2000
	s_nop 0
	global_load_lds_dwordx4 v134, s[14:15]
	s_mov_b32 m0, s26
	s_nop 0
	global_load_lds_dwordx4 v130, s[100:101]
	s_mov_b32 m0, s27
	s_nop 0
	global_load_lds_dwordx4 v132, s[100:101]
	s_waitcnt vmcnt(8) lgkmcnt(0)
	s_barrier
	s_setprio 1
	v_mfma_f32_16x16x32_bf16 v[62:65], v[144:147], v[182:185], v[62:65]
	v_mfma_f32_16x16x32_bf16 v[58:61], v[152:155], v[182:185], v[58:61]
	v_mfma_f32_16x16x32_bf16 v[54:57], v[144:147], v[190:193], v[54:57]
	v_mfma_f32_16x16x32_bf16 v[50:53], v[152:155], v[190:193], v[50:53]
	v_mfma_f32_16x16x32_bf16 v[38:41], v[144:147], v[200:203], v[38:41]
	v_mfma_f32_16x16x32_bf16 v[34:37], v[152:155], v[200:203], v[34:37]
	v_mfma_f32_16x16x32_bf16 v[22:25], v[144:147], v[208:211], v[22:25]
	v_mfma_f32_16x16x32_bf16 v[18:21], v[152:155], v[208:211], v[18:21]
	v_mfma_f32_16x16x32_bf16 v[62:65], v[148:151], v[186:189], v[62:65]
	v_mfma_f32_16x16x32_bf16 v[58:61], v[156:159], v[186:189], v[58:61]
	v_mfma_f32_16x16x32_bf16 v[54:57], v[148:151], v[194:197], v[54:57]
	v_mfma_f32_16x16x32_bf16 v[50:53], v[156:159], v[194:197], v[50:53]
	v_mfma_f32_16x16x32_bf16 v[38:41], v[148:151], v[204:207], v[38:41]
	v_mfma_f32_16x16x32_bf16 v[34:37], v[156:159], v[204:207], v[34:37]
	v_mfma_f32_16x16x32_bf16 v[22:25], v[148:151], v[212:215], v[22:25]
	v_mfma_f32_16x16x32_bf16 v[18:21], v[156:159], v[212:215], v[18:21]
	s_setprio 0
	s_setprio 1
	v_mfma_f32_16x16x32_bf16 v[46:49], v[166:169], v[182:185], v[46:49]
	v_mfma_f32_16x16x32_bf16 v[42:45], v[174:177], v[182:185], v[42:45]
	v_mfma_f32_16x16x32_bf16 v[30:33], v[166:169], v[190:193], v[30:33]
	v_mfma_f32_16x16x32_bf16 v[26:29], v[174:177], v[190:193], v[26:29]
	v_mfma_f32_16x16x32_bf16 v[14:17], v[166:169], v[200:203], v[14:17]
	v_mfma_f32_16x16x32_bf16 v[10:13], v[174:177], v[200:203], v[10:13]
	v_mfma_f32_16x16x32_bf16 v[6:9], v[166:169], v[208:211], v[6:9]
	v_mfma_f32_16x16x32_bf16 v[2:5], v[174:177], v[208:211], v[2:5]
	v_mfma_f32_16x16x32_bf16 v[46:49], v[170:173], v[186:189], v[46:49]
	v_mfma_f32_16x16x32_bf16 v[42:45], v[178:181], v[186:189], v[42:45]
	v_mfma_f32_16x16x32_bf16 v[30:33], v[170:173], v[194:197], v[30:33]
	v_mfma_f32_16x16x32_bf16 v[26:29], v[178:181], v[194:197], v[26:29]
	v_mfma_f32_16x16x32_bf16 v[14:17], v[170:173], v[204:207], v[14:17]
	v_mfma_f32_16x16x32_bf16 v[10:13], v[178:181], v[204:207], v[10:13]
	v_mfma_f32_16x16x32_bf16 v[6:9], v[170:173], v[212:215], v[6:9]
	v_mfma_f32_16x16x32_bf16 v[2:5], v[178:181], v[212:215], v[2:5]
	s_setprio 0
	s_barrier
	s_add_i32 s42, s42, 2
	s_add_u32 s10, s10, 0x100
	s_addc_u32 s11, s11, 0
	s_add_u32 s18, s18, 0x100
	s_addc_u32 s33, s33, 0
	s_cmp_gt_u32 s42, 29
	s_cbranch_scc0 .LBB0_290
	s_and_b64 vcc, exec, s[2:3]
	s_cbranch_vccz .LBB0_293
	s_barrier

; #define PG8_STAGE(bufoff, gbase, voff) do { _Pragma("unroll") for (int _i = 0; _i < 2; ++_i) \
;         __builtin_amdgcn_global_load_lds((const unsigned*)((const char*)(gbase) + (voff)[_i]), (LAS unsigned*)(lds + (bufoff) + ldsw + _i * 8192), 16, 0, 0); } while (0)
; #define PG8_LDA(dst, b, h) do { _Pragma("unroll") for (int m = 0; m < 4; ++m) _Pragma("unroll") for (int k = 0; k < 2; ++k) dst[m][k] = *(const LAS bf16x8*)(lds + PG8_SA(b, h) + aoff + m * 2048 + k * 1024); } while (0)
; #define PG8_LDB(dst, b, h) do { _Pragma("unroll") for (int n = 0; n < 2; ++n) _Pragma("unroll") for (int k = 0; k < 2; ++k) dst[n][k] = *(const LAS bf16x8*)(lds + PG8_SB(b, h) + boff + n * 2048 + k * 1024); } while (0)
; #define PG8_MMA(ai, bj, At, Bt) do { __builtin_amdgcn_s_setprio(1); _Pragma("unroll") for (int m = 0; m < 4; ++m) _Pragma("unroll") for (int n = 0; n < 2; ++n) _Pragma("unroll") for (int k = 0; k < 2; ++k) \
;         acc[ai][bj][m][n] = __builtin_amdgcn_mfma_f32_16x16x32_bf16(Bt[n][k], At[m][k], acc[ai][bj][m][n], 0, 0, 0); __builtin_amdgcn_s_setprio(0); } while (0)
; #define PG8_WAIT_V(n) asm volatile("s_waitcnt vmcnt(" #n ")" ::: "memory")
; #define PG8_WAIT_L(n) asm volatile("s_waitcnt lgkmcnt(" #n ")" ::: "memory")
; #define PG8_BAR __builtin_amdgcn_s_barrier()
; #define PG8_SCHED __builtin_amdgcn_sched_barrier(0)
; template <class Epi, class Sched>
; __device__ __forceinline__ void gemm_phase(LAS unsigned char* lds, const int lda, const int ldb, const int K, const Sched& S, const Epi& E, int tid) {
;     ...
;         for (int t = 0; t < nt; t += 2) {
;             const bool last = (t == nt - 2);
;             const char* a1 = cA + (size_t)(t + 1) * kstep;
;             const char* a2 = last ? nA : cA + (size_t)(t + 2) * kstep; const char* b2 = last ? nB : cB + (size_t)(t + 2) * kstep;
;             const char* a3 = a2 + kstep; const char* b3 = b2 + kstep;
;             PG8_LDB(B0, 0, 0); PG8_LDB(B1, 0, 1); PG8_SCHED; PG8_LDA(At, 0, 0); PG8_STAGE(PG8_SA(1, 1), a1 + hA, voffA);
;             PG8_WAIT_V(8); PG8_WAIT_L(0); PG8_BAR; PG8_MMA(0, 0, At, B0); PG8_MMA(0, 1, At, B1); PG8_BAR; PG8_SCHED;
;             PG8_LDA(At, 0, 1); PG8_STAGE(PG8_SB(0, 0), b2, voffB); PG8_STAGE(PG8_SB(0, 1), b2 + hB, voffB); PG8_STAGE(PG8_SA(0, 0), a2, voffA);
;             PG8_WAIT_V(8); PG8_WAIT_L(0); PG8_BAR; PG8_MMA(1, 0, At, B0); PG8_MMA(1, 1, At, B1); PG8_BAR; PG8_SCHED;
.LBB0_448:
	s_add_u32 s10, s8, 0x100
	s_addc_u32 s11, s9, 0
	s_add_i32 s34, 0, 0x10000
	s_cmp_eq_u32 s44, 2
	s_cselect_b32 s17, s5, s11
	s_cselect_b32 s16, s4, s10
	s_cselect_b32 s15, s7, s43
	s_cselect_b32 s14, s6, s42
	s_add_i32 s35, 0, 0x14000
	v_add_u32_e32 v152, s34, v157
	v_add_u32_e32 v172, s35, v157
	ds_read_b128 v[130:133], v152
	ds_read_b128 v[134:137], v152 offset:1024
	ds_read_b128 v[148:151], v152 offset:2048
	ds_read_b128 v[152:155], v152 offset:3072
	ds_read_b128 v[160:163], v172
	ds_read_b128 v[164:167], v172 offset:1024
	ds_read_b128 v[168:171], v172 offset:2048
	ds_read_b128 v[172:175], v172 offset:3072
	s_add_i32 m0, s19, 0xc000
	ds_read_b128 v[176:179], v159
	ds_read_b128 v[180:183], v159 offset:1024
	ds_read_b128 v[184:187], v159 offset:2048
	ds_read_b128 v[188:191], v159 offset:3072
	ds_read_b128 v[192:195], v159 offset:4096
	ds_read_b128 v[200:203], v159 offset:5120
	ds_read_b128 v[204:207], v159 offset:6144
	ds_read_b128 v[208:211], v159 offset:7168
	global_load_lds_dwordx4 v144, s[8:9]
	s_add_i32 m0, s19, 0xe000
	s_nop 0
	global_load_lds_dwordx4 v146, s[8:9]
	s_waitcnt vmcnt(8) lgkmcnt(0)
	s_barrier
	s_setprio 1
	v_mfma_f32_16x16x32_bf16 v[126:129], v[130:133], v[176:179], v[126:129]
	v_mfma_f32_16x16x32_bf16 v[122:125], v[148:151], v[176:179], v[122:125]
	v_mfma_f32_16x16x32_bf16 v[118:121], v[130:133], v[184:187], v[118:121]
	v_mfma_f32_16x16x32_bf16 v[114:117], v[148:151], v[184:187], v[114:117]
	v_mfma_f32_16x16x32_bf16 v[110:113], v[130:133], v[192:195], v[110:113]
	v_mfma_f32_16x16x32_bf16 v[106:109], v[148:151], v[192:195], v[106:109]
	v_mfma_f32_16x16x32_bf16 v[102:105], v[130:133], v[204:207], v[102:105]
	v_mfma_f32_16x16x32_bf16 v[98:101], v[148:151], v[204:207], v[98:101]
	v_mfma_f32_16x16x32_bf16 v[126:129], v[134:137], v[180:183], v[126:129]
	v_mfma_f32_16x16x32_bf16 v[122:125], v[152:155], v[180:183], v[122:125]
	v_mfma_f32_16x16x32_bf16 v[118:121], v[134:137], v[188:191], v[118:121]
	v_mfma_f32_16x16x32_bf16 v[114:117], v[152:155], v[188:191], v[114:117]
	v_mfma_f32_16x16x32_bf16 v[110:113], v[134:137], v[200:203], v[110:113]
	v_mfma_f32_16x16x32_bf16 v[106:109], v[152:155], v[200:203], v[106:109]
	v_mfma_f32_16x16x32_bf16 v[102:105], v[134:137], v[208:211], v[102:105]
	v_mfma_f32_16x16x32_bf16 v[98:101], v[152:155], v[208:211], v[98:101]
	s_setprio 0
	s_setprio 1
	v_mfma_f32_16x16x32_bf16 v[74:77], v[160:163], v[176:179], v[74:77]
	v_mfma_f32_16x16x32_bf16 v[66:69], v[168:171], v[176:179], v[66:69]
	v_mfma_f32_16x16x32_bf16 v[54:57], v[160:163], v[184:187], v[54:57]
	v_mfma_f32_16x16x32_bf16 v[50:53], v[168:171], v[184:187], v[50:53]
	v_mfma_f32_16x16x32_bf16 v[46:49], v[160:163], v[192:195], v[46:49]
	v_mfma_f32_16x16x32_bf16 v[42:45], v[168:171], v[192:195], v[42:45]
	v_mfma_f32_16x16x32_bf16 v[38:41], v[160:163], v[204:207], v[38:41]
	v_mfma_f32_16x16x32_bf16 v[34:37], v[168:171], v[204:207], v[34:37]
	v_mfma_f32_16x16x32_bf16 v[74:77], v[164:167], v[180:183], v[74:77]
	v_mfma_f32_16x16x32_bf16 v[66:69], v[172:175], v[180:183], v[66:69]
	v_mfma_f32_16x16x32_bf16 v[54:57], v[164:167], v[188:191], v[54:57]
	v_mfma_f32_16x16x32_bf16 v[50:53], v[172:175], v[188:191], v[50:53]
	v_mfma_f32_16x16x32_bf16 v[46:49], v[164:167], v[200:203], v[46:49]
	v_mfma_f32_16x16x32_bf16 v[42:45], v[172:175], v[200:203], v[42:45]
	v_mfma_f32_16x16x32_bf16 v[38:41], v[164:167], v[208:211], v[38:41]
	v_mfma_f32_16x16x32_bf16 v[34:37], v[172:175], v[208:211], v[34:37]
	s_setprio 0
	s_barrier
	s_add_u32 s98, s14, s30
	s_addc_u32 s99, s15, s31
	s_add_u32 s100, s16, s30
	s_addc_u32 s101, s17, s31
	s_add_i32 s8, s34, s18
	s_mov_b32 m0, s8
	ds_read_b128 v[176:179], v159 offset:16384
	ds_read_b128 v[180:183], v159 offset:17408
	ds_read_b128 v[184:187], v159 offset:18432
	ds_read_b128 v[188:191], v159 offset:19456
	ds_read_b128 v[192:195], v159 offset:20480
	ds_read_b128 v[200:203], v159 offset:21504
	ds_read_b128 v[204:207], v159 offset:22528
	ds_read_b128 v[208:211], v159 offset:23552
	global_load_lds_dwordx4 v0, s[14:15]
	s_add_i32 m0, s8, 0x2000
	s_add_u32 s8, s14, 0x18000
	s_addc_u32 s9, s15, 0
	s_add_i32 s34, s35, s18
	global_load_lds_dwordx4 v142, s[14:15]
	s_mov_b32 m0, s34
	s_nop 0
	global_load_lds_dwordx4 v0, s[8:9]
	s_add_i32 m0, s34, 0x2000
	s_nop 0
	global_load_lds_dwordx4 v142, s[8:9]
	s_mov_b32 m0, s19
	s_nop 0
	global_load_lds_dwordx4 v138, s[16:17]
	s_mov_b32 m0, s20
	s_nop 0
	global_load_lds_dwordx4 v140, s[16:17]
	s_waitcnt vmcnt(8) lgkmcnt(0)
	s_barrier
	s_setprio 1
	v_mfma_f32_16x16x32_bf16 v[94:97], v[130:133], v[176:179], v[94:97]
	v_mfma_f32_16x16x32_bf16 v[90:93], v[148:151], v[176:179], v[90:93]
	v_mfma_f32_16x16x32_bf16 v[86:89], v[130:133], v[184:187], v[86:89]
	v_mfma_f32_16x16x32_bf16 v[82:85], v[148:151], v[184:187], v[82:85]
	v_mfma_f32_16x16x32_bf16 v[78:81], v[130:133], v[192:195], v[78:81]
	v_mfma_f32_16x16x32_bf16 v[70:73], v[148:151], v[192:195], v[70:73]
	v_mfma_f32_16x16x32_bf16 v[62:65], v[130:133], v[204:207], v[62:65]
	v_mfma_f32_16x16x32_bf16 v[58:61], v[148:151], v[204:207], v[58:61]
	v_mfma_f32_16x16x32_bf16 v[94:97], v[134:137], v[180:183], v[94:97]
	v_mfma_f32_16x16x32_bf16 v[90:93], v[152:155], v[180:183], v[90:93]
	v_mfma_f32_16x16x32_bf16 v[86:89], v[134:137], v[188:191], v[86:89]
	v_mfma_f32_16x16x32_bf16 v[82:85], v[152:155], v[188:191], v[82:85]
	v_mfma_f32_16x16x32_bf16 v[78:81], v[134:137], v[200:203], v[78:81]
	v_mfma_f32_16x16x32_bf16 v[70:73], v[152:155], v[200:203], v[70:73]
	v_mfma_f32_16x16x32_bf16 v[62:65], v[134:137], v[208:211], v[62:65]
	v_mfma_f32_16x16x32_bf16 v[58:61], v[152:155], v[208:211], v[58:61]
	s_setprio 0
	s_setprio 1
	v_mfma_f32_16x16x32_bf16 v[30:33], v[160:163], v[176:179], v[30:33]
	v_mfma_f32_16x16x32_bf16 v[26:29], v[168:171], v[176:179], v[26:29]
	v_mfma_f32_16x16x32_bf16 v[22:25], v[160:163], v[184:187], v[22:25]
	v_mfma_f32_16x16x32_bf16 v[18:21], v[168:171], v[184:187], v[18:21]
	v_mfma_f32_16x16x32_bf16 v[14:17], v[160:163], v[192:195], v[14:17]
	v_mfma_f32_16x16x32_bf16 v[10:13], v[168:171], v[192:195], v[10:13]
	v_mfma_f32_16x16x32_bf16 v[6:9], v[160:163], v[204:207], v[6:9]
	v_mfma_f32_16x16x32_bf16 v[2:5], v[168:171], v[204:207], v[2:5]
	v_mfma_f32_16x16x32_bf16 v[30:33], v[164:167], v[180:183], v[30:33]
	v_mfma_f32_16x16x32_bf16 v[26:29], v[172:175], v[180:183], v[26:29]
	v_mfma_f32_16x16x32_bf16 v[22:25], v[164:167], v[188:191], v[22:25]
	v_mfma_f32_16x16x32_bf16 v[18:21], v[172:175], v[188:191], v[18:21]
	v_mfma_f32_16x16x32_bf16 v[14:17], v[164:167], v[200:203], v[14:17]
	v_mfma_f32_16x16x32_bf16 v[10:13], v[172:175], v[200:203], v[10:13]
	v_mfma_f32_16x16x32_bf16 v[6:9], v[164:167], v[208:211], v[6:9]
	v_mfma_f32_16x16x32_bf16 v[2:5], v[172:175], v[208:211], v[2:5]
	s_setprio 0
	s_barrier
; #define PG8_STAGE(bufoff, gbase, voff) do { _Pragma("unroll") for (int _i = 0; _i < 2; ++_i) \
;         __builtin_amdgcn_global_load_lds((const unsigned*)((const char*)(gbase) + (voff)[_i]), (LAS unsigned*)(lds + (bufoff) + ldsw + _i * 8192), 16, 0, 0); } while (0)
; #define PG8_LDA(dst, b, h) do { _Pragma("unroll") for (int m = 0; m < 4; ++m) _Pragma("unroll") for (int k = 0; k < 2; ++k) dst[m][k] = *(const LAS bf16x8*)(lds + PG8_SA(b, h) + aoff + m * 2048 + k * 1024); } while (0)
; #define PG8_LDB(dst, b, h) do { _Pragma("unroll") for (int n = 0; n < 2; ++n) _Pragma("unroll") for (int k = 0; k < 2; ++k) dst[n][k] = *(const LAS bf16x8*)(lds + PG8_SB(b, h) + boff + n * 2048 + k * 1024); } while (0)
; #define PG8_MMA(ai, bj, At, Bt) do { __builtin_amdgcn_s_setprio(1); _Pragma("unroll") for (int m = 0; m < 4; ++m) _Pragma("unroll") for (int n = 0; n < 2; ++n) _Pragma("unroll") for (int k = 0; k < 2; ++k) \
;         acc[ai][bj][m][n] = __builtin_amdgcn_mfma_f32_16x16x32_bf16(Bt[n][k], At[m][k], acc[ai][bj][m][n], 0, 0, 0); __builtin_amdgcn_s_setprio(0); } while (0)
; #define PG8_WAIT_V(n) asm volatile("s_waitcnt vmcnt(" #n ")" ::: "memory")
; #define PG8_WAIT_L(n) asm volatile("s_waitcnt lgkmcnt(" #n ")" ::: "memory")
; #define PG8_BAR __builtin_amdgcn_s_barrier()
; #define PG8_SCHED __builtin_amdgcn_sched_barrier(0)
; template <class Epi, class Sched>
; __device__ __forceinline__ void gemm_phase(LAS unsigned char* lds, const int lda, const int ldb, const int K, const Sched& S, const Epi& E, int tid) {
;     ...
;             PG8_LDB(B0, 1, 0); PG8_LDB(B1, 1, 1); PG8_SCHED; PG8_LDA(At, 1, 0); PG8_STAGE(PG8_SA(0, 1), a2 + hA, voffA);
;             PG8_WAIT_V(8); PG8_WAIT_L(0); PG8_BAR; PG8_MMA(0, 0, At, B0); PG8_MMA(0, 1, At, B1); PG8_BAR; PG8_SCHED;
;             PG8_LDA(At, 1, 1); PG8_STAGE(PG8_SB(1, 0), b3, voffB); PG8_STAGE(PG8_SB(1, 1), b3 + hB, voffB); PG8_STAGE(PG8_SA(1, 0), a3, voffA);
;             PG8_WAIT_V(8); PG8_WAIT_L(0); PG8_BAR; PG8_MMA(1, 0, At, B0); PG8_MMA(1, 1, At, B1); PG8_BAR; PG8_SCHED;
;         }
;         if (wr == 0) PG8_BAR;
	s_add_i32 s34, 0, 0x18000
	s_add_i32 s35, 0, 0x1c000
	v_add_u32_e32 v152, s34, v157
	v_add_u32_e32 v172, s35, v157
	ds_read_b128 v[130:133], v152
	ds_read_b128 v[134:137], v152 offset:1024
	ds_read_b128 v[148:151], v152 offset:2048
	ds_read_b128 v[152:155], v152 offset:3072
	ds_read_b128 v[160:163], v172
	ds_read_b128 v[164:167], v172 offset:1024
	ds_read_b128 v[168:171], v172 offset:2048
	ds_read_b128 v[172:175], v172 offset:3072
	s_add_u32 s8, s16, 0x60000
	s_addc_u32 s9, s17, 0
	s_mov_b32 m0, s21
	ds_read_b128 v[176:179], v159 offset:32768
	ds_read_b128 v[180:183], v159 offset:33792
	ds_read_b128 v[184:187], v159 offset:34816
	ds_read_b128 v[188:191], v159 offset:35840
	ds_read_b128 v[192:195], v159 offset:36864
	ds_read_b128 v[200:203], v159 offset:37888
	ds_read_b128 v[204:207], v159 offset:38912
	ds_read_b128 v[208:211], v159 offset:39936
	global_load_lds_dwordx4 v138, s[8:9]
	s_mov_b32 m0, s22
	s_nop 0
	global_load_lds_dwordx4 v140, s[8:9]
	s_waitcnt vmcnt(8) lgkmcnt(0)
	s_barrier
	s_setprio 1
	v_mfma_f32_16x16x32_bf16 v[126:129], v[130:133], v[176:179], v[126:129]
	v_mfma_f32_16x16x32_bf16 v[122:125], v[148:151], v[176:179], v[122:125]
	v_mfma_f32_16x16x32_bf16 v[118:121], v[130:133], v[184:187], v[118:121]
	v_mfma_f32_16x16x32_bf16 v[114:117], v[148:151], v[184:187], v[114:117]
	v_mfma_f32_16x16x32_bf16 v[110:113], v[130:133], v[192:195], v[110:113]
	v_mfma_f32_16x16x32_bf16 v[106:109], v[148:151], v[192:195], v[106:109]
	v_mfma_f32_16x16x32_bf16 v[102:105], v[130:133], v[204:207], v[102:105]
	v_mfma_f32_16x16x32_bf16 v[98:101], v[148:151], v[204:207], v[98:101]
	v_mfma_f32_16x16x32_bf16 v[126:129], v[134:137], v[180:183], v[126:129]
	v_mfma_f32_16x16x32_bf16 v[122:125], v[152:155], v[180:183], v[122:125]
	v_mfma_f32_16x16x32_bf16 v[118:121], v[134:137], v[188:191], v[118:121]
	v_mfma_f32_16x16x32_bf16 v[114:117], v[152:155], v[188:191], v[114:117]
	v_mfma_f32_16x16x32_bf16 v[110:113], v[134:137], v[200:203], v[110:113]
	v_mfma_f32_16x16x32_bf16 v[106:109], v[152:155], v[200:203], v[106:109]
	v_mfma_f32_16x16x32_bf16 v[102:105], v[134:137], v[208:211], v[102:105]
	v_mfma_f32_16x16x32_bf16 v[98:101], v[152:155], v[208:211], v[98:101]
	s_setprio 0
	s_setprio 1
	v_mfma_f32_16x16x32_bf16 v[74:77], v[160:163], v[176:179], v[74:77]
	v_mfma_f32_16x16x32_bf16 v[66:69], v[168:171], v[176:179], v[66:69]
	v_mfma_f32_16x16x32_bf16 v[54:57], v[160:163], v[184:187], v[54:57]
	v_mfma_f32_16x16x32_bf16 v[50:53], v[168:171], v[184:187], v[50:53]
	v_mfma_f32_16x16x32_bf16 v[46:49], v[160:163], v[192:195], v[46:49]
	v_mfma_f32_16x16x32_bf16 v[42:45], v[168:171], v[192:195], v[42:45]
	v_mfma_f32_16x16x32_bf16 v[38:41], v[160:163], v[204:207], v[38:41]
	v_mfma_f32_16x16x32_bf16 v[34:37], v[168:171], v[204:207], v[34:37]
	v_mfma_f32_16x16x32_bf16 v[74:77], v[164:167], v[180:183], v[74:77]
	v_mfma_f32_16x16x32_bf16 v[66:69], v[172:175], v[180:183], v[66:69]
	v_mfma_f32_16x16x32_bf16 v[54:57], v[164:167], v[188:191], v[54:57]
	v_mfma_f32_16x16x32_bf16 v[50:53], v[172:175], v[188:191], v[50:53]
	v_mfma_f32_16x16x32_bf16 v[46:49], v[164:167], v[200:203], v[46:49]
	v_mfma_f32_16x16x32_bf16 v[42:45], v[172:175], v[200:203], v[42:45]
	v_mfma_f32_16x16x32_bf16 v[38:41], v[164:167], v[208:211], v[38:41]
	v_mfma_f32_16x16x32_bf16 v[34:37], v[172:175], v[208:211], v[34:37]
	s_setprio 0
	s_barrier
	s_add_i32 s8, s34, s18
	s_mov_b32 m0, s8
	ds_read_b128 v[176:179], v159 offset:49152
	ds_read_b128 v[180:183], v159 offset:50176
	ds_read_b128 v[184:187], v159 offset:51200
	ds_read_b128 v[188:191], v159 offset:52224
	ds_read_b128 v[192:195], v159 offset:53248
	ds_read_b128 v[200:203], v159 offset:54272
	ds_read_b128 v[204:207], v159 offset:55296
	ds_read_b128 v[208:211], v159 offset:56320
	global_load_lds_dwordx4 v0, s[98:99]
	s_add_i32 m0, s8, 0x2000
	s_add_u32 s8, s14, 0x18080
	s_addc_u32 s9, s15, 0
	s_add_i32 s14, s35, s18
	global_load_lds_dwordx4 v142, s[98:99]
	s_mov_b32 m0, s14
	s_nop 0
	global_load_lds_dwordx4 v0, s[8:9]
	s_add_i32 m0, s14, 0x2000
	s_nop 0
	global_load_lds_dwordx4 v142, s[8:9]
	s_mov_b32 m0, s23
	s_nop 0
	global_load_lds_dwordx4 v138, s[100:101]
	s_mov_b32 m0, s25
	s_nop 0
	global_load_lds_dwordx4 v140, s[100:101]
	s_waitcnt vmcnt(8) lgkmcnt(0)
	s_barrier
	s_setprio 1
	v_mfma_f32_16x16x32_bf16 v[94:97], v[130:133], v[176:179], v[94:97]
	v_mfma_f32_16x16x32_bf16 v[90:93], v[148:151], v[176:179], v[90:93]
	v_mfma_f32_16x16x32_bf16 v[86:89], v[130:133], v[184:187], v[86:89]
	v_mfma_f32_16x16x32_bf16 v[82:85], v[148:151], v[184:187], v[82:85]
	v_mfma_f32_16x16x32_bf16 v[78:81], v[130:133], v[192:195], v[78:81]
	v_mfma_f32_16x16x32_bf16 v[70:73], v[148:151], v[192:195], v[70:73]
	v_mfma_f32_16x16x32_bf16 v[62:65], v[130:133], v[204:207], v[62:65]
	v_mfma_f32_16x16x32_bf16 v[58:61], v[148:151], v[204:207], v[58:61]
	v_mfma_f32_16x16x32_bf16 v[94:97], v[134:137], v[180:183], v[94:97]
	v_mfma_f32_16x16x32_bf16 v[90:93], v[152:155], v[180:183], v[90:93]
	v_mfma_f32_16x16x32_bf16 v[86:89], v[134:137], v[188:191], v[86:89]
	v_mfma_f32_16x16x32_bf16 v[82:85], v[152:155], v[188:191], v[82:85]
	v_mfma_f32_16x16x32_bf16 v[78:81], v[134:137], v[200:203], v[78:81]
	v_mfma_f32_16x16x32_bf16 v[70:73], v[152:155], v[200:203], v[70:73]
	v_mfma_f32_16x16x32_bf16 v[62:65], v[134:137], v[208:211], v[62:65]
	v_mfma_f32_16x16x32_bf16 v[58:61], v[152:155], v[208:211], v[58:61]
	s_setprio 0
	s_setprio 1
	v_mfma_f32_16x16x32_bf16 v[30:33], v[160:163], v[176:179], v[30:33]
	v_mfma_f32_16x16x32_bf16 v[26:29], v[168:171], v[176:179], v[26:29]
	v_mfma_f32_16x16x32_bf16 v[22:25], v[160:163], v[184:187], v[22:25]
	v_mfma_f32_16x16x32_bf16 v[18:21], v[168:171], v[184:187], v[18:21]
	v_mfma_f32_16x16x32_bf16 v[14:17], v[160:163], v[192:195], v[14:17]
	v_mfma_f32_16x16x32_bf16 v[10:13], v[168:171], v[192:195], v[10:13]
	v_mfma_f32_16x16x32_bf16 v[6:9], v[160:163], v[204:207], v[6:9]
	v_mfma_f32_16x16x32_bf16 v[2:5], v[168:171], v[204:207], v[2:5]
	v_mfma_f32_16x16x32_bf16 v[30:33], v[164:167], v[180:183], v[30:33]
	v_mfma_f32_16x16x32_bf16 v[26:29], v[172:175], v[180:183], v[26:29]
	v_mfma_f32_16x16x32_bf16 v[22:25], v[164:167], v[188:191], v[22:25]
	v_mfma_f32_16x16x32_bf16 v[18:21], v[172:175], v[188:191], v[18:21]
	v_mfma_f32_16x16x32_bf16 v[14:17], v[164:167], v[200:203], v[14:17]
	v_mfma_f32_16x16x32_bf16 v[10:13], v[172:175], v[200:203], v[10:13]
	v_mfma_f32_16x16x32_bf16 v[6:9], v[164:167], v[208:211], v[6:9]
	v_mfma_f32_16x16x32_bf16 v[2:5], v[172:175], v[208:211], v[2:5]
	s_setprio 0
	s_barrier
	s_add_i32 s44, s44, 2
	s_add_u32 s42, s42, 0x100
	s_addc_u32 s43, s43, 0
	s_cmp_gt_u32 s44, 3
	s_mov_b64 s[8:9], s[10:11]
	s_cbranch_scc0 .LBB0_448
	s_and_b64 vcc, exec, s[2:3]
	s_cbranch_vccz .LBB0_451
	s_barrier

; #define PG8_STAGE(bufoff, gbase, voff) do { _Pragma("unroll") for (int _i = 0; _i < 2; ++_i) \
;         __builtin_amdgcn_global_load_lds((const unsigned*)((const char*)(gbase) + (voff)[_i]), (LAS unsigned*)(lds + (bufoff) + ldsw + _i * 8192), 16, 0, 0); } while (0)
; #define PG8_LDA(dst, b, h) do { _Pragma("unroll") for (int m = 0; m < 4; ++m) _Pragma("unroll") for (int k = 0; k < 2; ++k) dst[m][k] = *(const LAS bf16x8*)(lds + PG8_SA(b, h) + aoff + m * 2048 + k * 1024); } while (0)
; #define PG8_LDB(dst, b, h) do { _Pragma("unroll") for (int n = 0; n < 2; ++n) _Pragma("unroll") for (int k = 0; k < 2; ++k) dst[n][k] = *(const LAS bf16x8*)(lds + PG8_SB(b, h) + boff + n * 2048 + k * 1024); } while (0)
; #define PG8_MMA(ai, bj, At, Bt) do { __builtin_amdgcn_s_setprio(1); _Pragma("unroll") for (int m = 0; m < 4; ++m) _Pragma("unroll") for (int n = 0; n < 2; ++n) _Pragma("unroll") for (int k = 0; k < 2; ++k) \
;         acc[ai][bj][m][n] = __builtin_amdgcn_mfma_f32_16x16x32_bf16(Bt[n][k], At[m][k], acc[ai][bj][m][n], 0, 0, 0); __builtin_amdgcn_s_setprio(0); } while (0)
; #define PG8_WAIT_V(n) asm volatile("s_waitcnt vmcnt(" #n ")" ::: "memory")
; #define PG8_WAIT_L(n) asm volatile("s_waitcnt lgkmcnt(" #n ")" ::: "memory")
; #define PG8_BAR __builtin_amdgcn_s_barrier()
; #define PG8_SCHED __builtin_amdgcn_sched_barrier(0)
; template <class Epi, class Sched>
; __device__ __forceinline__ void gemm_phase(LAS unsigned char* lds, const int lda, const int ldb, const int K, const Sched& S, const Epi& E, int tid) {
;     ...
;         for (int t = 0; t < nt; t += 2) {
;             const bool last = (t == nt - 2);
;             const char* a1 = cA + (size_t)(t + 1) * kstep;
;             const char* a2 = last ? nA : cA + (size_t)(t + 2) * kstep; const char* b2 = last ? nB : cB + (size_t)(t + 2) * kstep;
;             const char* a3 = a2 + kstep; const char* b3 = b2 + kstep;
;             PG8_LDB(B0, 0, 0); PG8_LDB(B1, 0, 1); PG8_SCHED; PG8_LDA(At, 0, 0); PG8_STAGE(PG8_SA(1, 1), a1 + hA, voffA);
;             PG8_WAIT_V(8); PG8_WAIT_L(0); PG8_BAR; PG8_MMA(0, 0, At, B0); PG8_MMA(0, 1, At, B1); PG8_BAR; PG8_SCHED;
;             PG8_LDA(At, 0, 1); PG8_STAGE(PG8_SB(0, 0), b2, voffB); PG8_STAGE(PG8_SB(0, 1), b2 + hB, voffB); PG8_STAGE(PG8_SA(0, 0), a2, voffA);
;             PG8_WAIT_V(8); PG8_WAIT_L(0); PG8_BAR; PG8_MMA(1, 0, At, B0); PG8_MMA(1, 1, At, B1); PG8_BAR; PG8_SCHED;
.LBB0_530:
	s_add_u32 s8, s6, 0xfff80080
	s_addc_u32 s9, s7, -1
	s_add_i32 s16, 0, 0x10000
	s_cmp_eq_u32 s15, 28
	s_cselect_b32 s11, s53, s9
	s_cselect_b32 s10, s52, s8
	v_add_u32_e32 v106, s16, v208
	s_cselect_b32 s9, s55, s14
	s_cselect_b32 s8, s54, s3
	s_add_i32 s22, 0, 0x14000
	ds_read_b128 v[102:105], v106
	ds_read_b128 v[128:131], v106 offset:1024
	ds_read_b128 v[132:135], v106 offset:2048
	ds_read_b128 v[154:157], v106 offset:3072
	v_add_u32_e32 v106, s22, v208
	ds_read_b128 v[158:161], v106
	ds_read_b128 v[162:165], v106 offset:1024
	ds_read_b128 v[166:169], v106 offset:2048
	ds_read_b128 v[170:173], v106 offset:3072
	s_add_i32 m0, s20, 0xc000
	ds_read_b128 v[174:177], v210
	ds_read_b128 v[178:181], v210 offset:1024
	ds_read_b128 v[182:185], v210 offset:2048
	ds_read_b128 v[186:189], v210 offset:3072
	ds_read_b128 v[190:193], v210 offset:4096
	ds_read_b128 v[194:197], v210 offset:5120
	ds_read_b128 v[200:203], v210 offset:6144
	ds_read_b128 v[204:207], v210 offset:7168
	global_load_lds_dwordx4 v150, s[6:7]
	s_add_i32 m0, s20, 0xe000
	s_nop 0
	global_load_lds_dwordx4 v152, s[6:7]
	s_waitcnt vmcnt(8) lgkmcnt(0)
	s_barrier
	s_setprio 1
	v_mfma_f32_16x16x32_bf16 v[140:143], v[102:105], v[174:177], v[140:143]
	v_mfma_f32_16x16x32_bf16 v[94:97], v[132:135], v[174:177], v[94:97]
	v_mfma_f32_16x16x32_bf16 v[136:139], v[102:105], v[182:185], v[136:139]
	v_mfma_f32_16x16x32_bf16 v[90:93], v[132:135], v[182:185], v[90:93]
	v_mfma_f32_16x16x32_bf16 v[124:127], v[102:105], v[190:193], v[124:127]
	v_mfma_f32_16x16x32_bf16 v[86:89], v[132:135], v[190:193], v[86:89]
	v_mfma_f32_16x16x32_bf16 v[120:123], v[102:105], v[200:203], v[120:123]
	v_mfma_f32_16x16x32_bf16 v[82:85], v[132:135], v[200:203], v[82:85]
	v_mfma_f32_16x16x32_bf16 v[140:143], v[128:131], v[178:181], v[140:143]
	v_mfma_f32_16x16x32_bf16 v[94:97], v[154:157], v[178:181], v[94:97]
	v_mfma_f32_16x16x32_bf16 v[136:139], v[128:131], v[186:189], v[136:139]
	v_mfma_f32_16x16x32_bf16 v[90:93], v[154:157], v[186:189], v[90:93]
	v_mfma_f32_16x16x32_bf16 v[124:127], v[128:131], v[194:197], v[124:127]
	v_mfma_f32_16x16x32_bf16 v[86:89], v[154:157], v[194:197], v[86:89]
	v_mfma_f32_16x16x32_bf16 v[120:123], v[128:131], v[204:207], v[120:123]
	v_mfma_f32_16x16x32_bf16 v[82:85], v[154:157], v[204:207], v[82:85]
	s_setprio 0
	s_setprio 1
	v_mfma_f32_16x16x32_bf16 v[62:65], v[158:161], v[174:177], v[62:65]
	v_mfma_f32_16x16x32_bf16 v[34:37], v[166:169], v[174:177], v[34:37]
	v_mfma_f32_16x16x32_bf16 v[58:61], v[158:161], v[182:185], v[58:61]
	v_mfma_f32_16x16x32_bf16 v[26:29], v[166:169], v[182:185], v[26:29]
	v_mfma_f32_16x16x32_bf16 v[54:57], v[158:161], v[190:193], v[54:57]
	v_mfma_f32_16x16x32_bf16 v[22:25], v[166:169], v[190:193], v[22:25]
	v_mfma_f32_16x16x32_bf16 v[50:53], v[158:161], v[200:203], v[50:53]
	v_mfma_f32_16x16x32_bf16 v[18:21], v[166:169], v[200:203], v[18:21]
	v_mfma_f32_16x16x32_bf16 v[62:65], v[162:165], v[178:181], v[62:65]
	v_mfma_f32_16x16x32_bf16 v[34:37], v[170:173], v[178:181], v[34:37]
	v_mfma_f32_16x16x32_bf16 v[58:61], v[162:165], v[186:189], v[58:61]
	v_mfma_f32_16x16x32_bf16 v[26:29], v[170:173], v[186:189], v[26:29]
	v_mfma_f32_16x16x32_bf16 v[54:57], v[162:165], v[194:197], v[54:57]
	v_mfma_f32_16x16x32_bf16 v[22:25], v[170:173], v[194:197], v[22:25]
	v_mfma_f32_16x16x32_bf16 v[50:53], v[162:165], v[204:207], v[50:53]
	v_mfma_f32_16x16x32_bf16 v[18:21], v[170:173], v[204:207], v[18:21]
	s_setprio 0
	s_barrier
	s_add_u32 s98, s8, s30
	s_addc_u32 s99, s9, s31
	s_add_u32 s100, s10, s30
	s_addc_u32 s101, s11, s31
	s_add_i32 s16, s16, s5
	s_mov_b32 m0, s16
	ds_read_b128 v[174:177], v210 offset:16384
	ds_read_b128 v[178:181], v210 offset:17408
	ds_read_b128 v[182:185], v210 offset:18432
	ds_read_b128 v[186:189], v210 offset:19456
	ds_read_b128 v[190:193], v210 offset:20480
	ds_read_b128 v[194:197], v210 offset:21504
	ds_read_b128 v[200:203], v210 offset:22528
	ds_read_b128 v[204:207], v210 offset:23552
	global_load_lds_dwordx4 v0, s[8:9]
	s_add_i32 m0, s16, 0x2000
	s_add_u32 s16, s8, 0x80000
	s_addc_u32 s17, s9, 0
	s_add_i32 s22, s22, s5
	global_load_lds_dwordx4 v148, s[8:9]
	s_mov_b32 m0, s22
	s_nop 0
	global_load_lds_dwordx4 v0, s[16:17]
	s_add_i32 m0, s22, 0x2000
	s_nop 0
	global_load_lds_dwordx4 v148, s[16:17]
	s_mov_b32 m0, s20
	s_nop 0
	global_load_lds_dwordx4 v144, s[10:11]
	s_mov_b32 m0, s21
	s_nop 0
	global_load_lds_dwordx4 v146, s[10:11]
	s_waitcnt vmcnt(8) lgkmcnt(0)
	s_barrier
	s_setprio 1
	v_mfma_f32_16x16x32_bf16 v[116:119], v[102:105], v[174:177], v[116:119]
	v_mfma_f32_16x16x32_bf16 v[78:81], v[132:135], v[174:177], v[78:81]
	v_mfma_f32_16x16x32_bf16 v[112:115], v[102:105], v[182:185], v[112:115]
	v_mfma_f32_16x16x32_bf16 v[74:77], v[132:135], v[182:185], v[74:77]
	v_mfma_f32_16x16x32_bf16 v[106:109], v[102:105], v[190:193], v[108:111]
	v_mfma_f32_16x16x32_bf16 v[70:73], v[132:135], v[190:193], v[70:73]
	v_mfma_f32_16x16x32_bf16 v[98:101], v[102:105], v[200:203], v[98:101]
	v_mfma_f32_16x16x32_bf16 v[66:69], v[132:135], v[200:203], v[66:69]
	v_mfma_f32_16x16x32_bf16 v[116:119], v[128:131], v[178:181], v[116:119]
	v_mfma_f32_16x16x32_bf16 v[78:81], v[154:157], v[178:181], v[78:81]
	v_mfma_f32_16x16x32_bf16 v[112:115], v[128:131], v[186:189], v[112:115]
	v_mfma_f32_16x16x32_bf16 v[74:77], v[154:157], v[186:189], v[74:77]
	v_mfma_f32_16x16x32_bf16 v[106:109], v[128:131], v[194:197], v[106:109]
	v_mfma_f32_16x16x32_bf16 v[70:73], v[154:157], v[194:197], v[70:73]
	v_mfma_f32_16x16x32_bf16 v[98:101], v[128:131], v[204:207], v[98:101]
	v_mfma_f32_16x16x32_bf16 v[66:69], v[154:157], v[204:207], v[66:69]
	s_setprio 0
	s_setprio 1
	v_mfma_f32_16x16x32_bf16 v[46:49], v[158:161], v[174:177], v[46:49]
	v_mfma_f32_16x16x32_bf16 v[14:17], v[166:169], v[174:177], v[14:17]
	v_mfma_f32_16x16x32_bf16 v[42:45], v[158:161], v[182:185], v[42:45]
	v_mfma_f32_16x16x32_bf16 v[10:13], v[166:169], v[182:185], v[10:13]
	v_mfma_f32_16x16x32_bf16 v[38:41], v[158:161], v[190:193], v[38:41]
	v_mfma_f32_16x16x32_bf16 v[6:9], v[166:169], v[190:193], v[6:9]
	v_mfma_f32_16x16x32_bf16 v[30:33], v[158:161], v[200:203], v[30:33]
	v_mfma_f32_16x16x32_bf16 v[2:5], v[166:169], v[200:203], v[2:5]
	v_mfma_f32_16x16x32_bf16 v[46:49], v[162:165], v[178:181], v[46:49]
	v_mfma_f32_16x16x32_bf16 v[14:17], v[170:173], v[178:181], v[14:17]
	v_mfma_f32_16x16x32_bf16 v[42:45], v[162:165], v[186:189], v[42:45]
	v_mfma_f32_16x16x32_bf16 v[10:13], v[170:173], v[186:189], v[10:13]
	v_mfma_f32_16x16x32_bf16 v[38:41], v[162:165], v[194:197], v[38:41]
	v_mfma_f32_16x16x32_bf16 v[6:9], v[170:173], v[194:197], v[6:9]
	v_mfma_f32_16x16x32_bf16 v[30:33], v[162:165], v[204:207], v[30:33]
	v_mfma_f32_16x16x32_bf16 v[2:5], v[170:173], v[204:207], v[2:5]
	s_setprio 0
	s_barrier
; #define PG8_STAGE(bufoff, gbase, voff) do { _Pragma("unroll") for (int _i = 0; _i < 2; ++_i) \
;         __builtin_amdgcn_global_load_lds((const unsigned*)((const char*)(gbase) + (voff)[_i]), (LAS unsigned*)(lds + (bufoff) + ldsw + _i * 8192), 16, 0, 0); } while (0)
; #define PG8_LDA(dst, b, h) do { _Pragma("unroll") for (int m = 0; m < 4; ++m) _Pragma("unroll") for (int k = 0; k < 2; ++k) dst[m][k] = *(const LAS bf16x8*)(lds + PG8_SA(b, h) + aoff + m * 2048 + k * 1024); } while (0)
; #define PG8_LDB(dst, b, h) do { _Pragma("unroll") for (int n = 0; n < 2; ++n) _Pragma("unroll") for (int k = 0; k < 2; ++k) dst[n][k] = *(const LAS bf16x8*)(lds + PG8_SB(b, h) + boff + n * 2048 + k * 1024); } while (0)
; #define PG8_MMA(ai, bj, At, Bt) do { __builtin_amdgcn_s_setprio(1); _Pragma("unroll") for (int m = 0; m < 4; ++m) _Pragma("unroll") for (int n = 0; n < 2; ++n) _Pragma("unroll") for (int k = 0; k < 2; ++k) \
;         acc[ai][bj][m][n] = __builtin_amdgcn_mfma_f32_16x16x32_bf16(Bt[n][k], At[m][k], acc[ai][bj][m][n], 0, 0, 0); __builtin_amdgcn_s_setprio(0); } while (0)
; #define PG8_WAIT_V(n) asm volatile("s_waitcnt vmcnt(" #n ")" ::: "memory")
; #define PG8_WAIT_L(n) asm volatile("s_waitcnt lgkmcnt(" #n ")" ::: "memory")
; #define PG8_BAR __builtin_amdgcn_s_barrier()
; #define PG8_SCHED __builtin_amdgcn_sched_barrier(0)
; template <class Epi, class Sched>
; __device__ __forceinline__ void gemm_phase(LAS unsigned char* lds, const int lda, const int ldb, const int K, const Sched& S, const Epi& E, int tid) {
;     ...
;             PG8_LDB(B0, 1, 0); PG8_LDB(B1, 1, 1); PG8_SCHED; PG8_LDA(At, 1, 0); PG8_STAGE(PG8_SA(0, 1), a2 + hA, voffA);
;             PG8_WAIT_V(8); PG8_WAIT_L(0); PG8_BAR; PG8_MMA(0, 0, At, B0); PG8_MMA(0, 1, At, B1); PG8_BAR; PG8_SCHED;
;             PG8_LDA(At, 1, 1); PG8_STAGE(PG8_SB(1, 0), b3, voffB); PG8_STAGE(PG8_SB(1, 1), b3 + hB, voffB); PG8_STAGE(PG8_SA(1, 0), a3, voffA);
;             PG8_WAIT_V(8); PG8_WAIT_L(0); PG8_BAR; PG8_MMA(1, 0, At, B0); PG8_MMA(1, 1, At, B1); PG8_BAR; PG8_SCHED;
;         }
;         if (wr == 0) PG8_BAR;
	s_add_i32 s16, 0, 0x18000
	v_add_u32_e32 v110, s16, v208
	s_add_i32 s17, 0, 0x1c000
	ds_read_b128 v[102:105], v110
	ds_read_b128 v[128:131], v110 offset:1024
	ds_read_b128 v[132:135], v110 offset:2048
	ds_read_b128 v[154:157], v110 offset:3072
	v_add_u32_e32 v110, s17, v208
	ds_read_b128 v[158:161], v110
	ds_read_b128 v[162:165], v110 offset:1024
	ds_read_b128 v[166:169], v110 offset:2048
	ds_read_b128 v[170:173], v110 offset:3072
	s_add_u32 s10, s10, 0x80000
	s_addc_u32 s11, s11, 0
	s_mov_b32 m0, s26
	ds_read_b128 v[174:177], v210 offset:32768
	ds_read_b128 v[178:181], v210 offset:33792
	ds_read_b128 v[182:185], v210 offset:34816
	ds_read_b128 v[186:189], v210 offset:35840
	ds_read_b128 v[190:193], v210 offset:36864
	ds_read_b128 v[194:197], v210 offset:37888
	ds_read_b128 v[200:203], v210 offset:38912
	ds_read_b128 v[204:207], v210 offset:39936
	global_load_lds_dwordx4 v144, s[10:11]
	s_mov_b32 m0, s27
	s_nop 0
	global_load_lds_dwordx4 v146, s[10:11]
	s_waitcnt vmcnt(8) lgkmcnt(0)
	s_barrier
	s_setprio 1
	v_mfma_f32_16x16x32_bf16 v[140:143], v[102:105], v[174:177], v[140:143]
	v_mfma_f32_16x16x32_bf16 v[94:97], v[132:135], v[174:177], v[94:97]
	v_mfma_f32_16x16x32_bf16 v[136:139], v[102:105], v[182:185], v[136:139]
	v_mfma_f32_16x16x32_bf16 v[90:93], v[132:135], v[182:185], v[90:93]
	v_mfma_f32_16x16x32_bf16 v[124:127], v[102:105], v[190:193], v[124:127]
	v_mfma_f32_16x16x32_bf16 v[86:89], v[132:135], v[190:193], v[86:89]
	v_mfma_f32_16x16x32_bf16 v[120:123], v[102:105], v[200:203], v[120:123]
	v_mfma_f32_16x16x32_bf16 v[82:85], v[132:135], v[200:203], v[82:85]
	v_mfma_f32_16x16x32_bf16 v[140:143], v[128:131], v[178:181], v[140:143]
	v_mfma_f32_16x16x32_bf16 v[94:97], v[154:157], v[178:181], v[94:97]
	v_mfma_f32_16x16x32_bf16 v[136:139], v[128:131], v[186:189], v[136:139]
	v_mfma_f32_16x16x32_bf16 v[90:93], v[154:157], v[186:189], v[90:93]
	v_mfma_f32_16x16x32_bf16 v[124:127], v[128:131], v[194:197], v[124:127]
	v_mfma_f32_16x16x32_bf16 v[86:89], v[154:157], v[194:197], v[86:89]
	v_mfma_f32_16x16x32_bf16 v[120:123], v[128:131], v[204:207], v[120:123]
	v_mfma_f32_16x16x32_bf16 v[82:85], v[154:157], v[204:207], v[82:85]
	s_setprio 0
	s_setprio 1
	v_mfma_f32_16x16x32_bf16 v[62:65], v[158:161], v[174:177], v[62:65]
	v_mfma_f32_16x16x32_bf16 v[34:37], v[166:169], v[174:177], v[34:37]
	v_mfma_f32_16x16x32_bf16 v[58:61], v[158:161], v[182:185], v[58:61]
	v_mfma_f32_16x16x32_bf16 v[26:29], v[166:169], v[182:185], v[26:29]
	v_mfma_f32_16x16x32_bf16 v[54:57], v[158:161], v[190:193], v[54:57]
	v_mfma_f32_16x16x32_bf16 v[22:25], v[166:169], v[190:193], v[22:25]
	v_mfma_f32_16x16x32_bf16 v[50:53], v[158:161], v[200:203], v[50:53]
	v_mfma_f32_16x16x32_bf16 v[18:21], v[166:169], v[200:203], v[18:21]
	v_mfma_f32_16x16x32_bf16 v[62:65], v[162:165], v[178:181], v[62:65]
	v_mfma_f32_16x16x32_bf16 v[34:37], v[170:173], v[178:181], v[34:37]
	v_mfma_f32_16x16x32_bf16 v[58:61], v[162:165], v[186:189], v[58:61]
	v_mfma_f32_16x16x32_bf16 v[26:29], v[170:173], v[186:189], v[26:29]
	v_mfma_f32_16x16x32_bf16 v[54:57], v[162:165], v[194:197], v[54:57]
	v_mfma_f32_16x16x32_bf16 v[22:25], v[170:173], v[194:197], v[22:25]
	v_mfma_f32_16x16x32_bf16 v[50:53], v[162:165], v[204:207], v[50:53]
	v_mfma_f32_16x16x32_bf16 v[18:21], v[170:173], v[204:207], v[18:21]
	s_setprio 0
	s_barrier
	s_add_i32 s10, s16, s5
	s_mov_b32 m0, s10
	ds_read_b128 v[174:177], v210 offset:49152
	ds_read_b128 v[178:181], v210 offset:50176
	ds_read_b128 v[182:185], v210 offset:51200
	ds_read_b128 v[186:189], v210 offset:52224
	ds_read_b128 v[190:193], v210 offset:53248
	ds_read_b128 v[194:197], v210 offset:54272
	ds_read_b128 v[200:203], v210 offset:55296
	ds_read_b128 v[204:207], v210 offset:56320
	global_load_lds_dwordx4 v0, s[98:99]
	s_add_i32 m0, s10, 0x2000
	s_add_u32 s8, s8, 0x80080
	s_addc_u32 s9, s9, 0
	s_add_i32 s10, s17, s5
	global_load_lds_dwordx4 v148, s[98:99]
	s_mov_b32 m0, s10
	s_nop 0
	global_load_lds_dwordx4 v0, s[8:9]
	s_add_i32 m0, s10, 0x2000
	s_nop 0
	global_load_lds_dwordx4 v148, s[8:9]
	s_mov_b32 m0, s25
	s_nop 0
	global_load_lds_dwordx4 v144, s[100:101]
	s_mov_b32 m0, s56
	s_nop 0
	global_load_lds_dwordx4 v146, s[100:101]
	s_waitcnt vmcnt(8) lgkmcnt(0)
	s_barrier
	s_setprio 1
	v_mfma_f32_16x16x32_bf16 v[116:119], v[102:105], v[174:177], v[116:119]
	v_mfma_f32_16x16x32_bf16 v[78:81], v[132:135], v[174:177], v[78:81]
	v_mfma_f32_16x16x32_bf16 v[110:113], v[102:105], v[182:185], v[112:115]
	v_mfma_f32_16x16x32_bf16 v[74:77], v[132:135], v[182:185], v[74:77]
	v_mfma_f32_16x16x32_bf16 v[106:109], v[102:105], v[190:193], v[106:109]
	v_mfma_f32_16x16x32_bf16 v[70:73], v[132:135], v[190:193], v[70:73]
	v_mfma_f32_16x16x32_bf16 v[98:101], v[102:105], v[200:203], v[98:101]
	v_mfma_f32_16x16x32_bf16 v[66:69], v[132:135], v[200:203], v[66:69]
	v_mfma_f32_16x16x32_bf16 v[116:119], v[128:131], v[178:181], v[116:119]
	v_mfma_f32_16x16x32_bf16 v[78:81], v[154:157], v[178:181], v[78:81]
	v_mfma_f32_16x16x32_bf16 v[112:115], v[128:131], v[186:189], v[110:113]
	v_mfma_f32_16x16x32_bf16 v[74:77], v[154:157], v[186:189], v[74:77]
	v_mfma_f32_16x16x32_bf16 v[108:111], v[128:131], v[194:197], v[106:109]
	v_mfma_f32_16x16x32_bf16 v[70:73], v[154:157], v[194:197], v[70:73]
	v_mfma_f32_16x16x32_bf16 v[98:101], v[128:131], v[204:207], v[98:101]
	v_mfma_f32_16x16x32_bf16 v[66:69], v[154:157], v[204:207], v[66:69]
	s_setprio 0
	s_setprio 1
	v_mfma_f32_16x16x32_bf16 v[46:49], v[158:161], v[174:177], v[46:49]
	v_mfma_f32_16x16x32_bf16 v[14:17], v[166:169], v[174:177], v[14:17]
	v_mfma_f32_16x16x32_bf16 v[42:45], v[158:161], v[182:185], v[42:45]
	v_mfma_f32_16x16x32_bf16 v[10:13], v[166:169], v[182:185], v[10:13]
	v_mfma_f32_16x16x32_bf16 v[38:41], v[158:161], v[190:193], v[38:41]
	v_mfma_f32_16x16x32_bf16 v[6:9], v[166:169], v[190:193], v[6:9]
	v_mfma_f32_16x16x32_bf16 v[30:33], v[158:161], v[200:203], v[30:33]
	v_mfma_f32_16x16x32_bf16 v[2:5], v[166:169], v[200:203], v[2:5]
	v_mfma_f32_16x16x32_bf16 v[46:49], v[162:165], v[178:181], v[46:49]
	v_mfma_f32_16x16x32_bf16 v[14:17], v[170:173], v[178:181], v[14:17]
	v_mfma_f32_16x16x32_bf16 v[42:45], v[162:165], v[186:189], v[42:45]
	v_mfma_f32_16x16x32_bf16 v[10:13], v[170:173], v[186:189], v[10:13]
	v_mfma_f32_16x16x32_bf16 v[38:41], v[162:165], v[194:197], v[38:41]
	v_mfma_f32_16x16x32_bf16 v[6:9], v[170:173], v[194:197], v[6:9]
	v_mfma_f32_16x16x32_bf16 v[30:33], v[162:165], v[204:207], v[30:33]
	v_mfma_f32_16x16x32_bf16 v[2:5], v[170:173], v[204:207], v[2:5]
	s_setprio 0
	s_barrier
	s_add_i32 s15, s15, 2
	s_add_u32 s6, s6, 0x100
	s_addc_u32 s7, s7, 0
	s_add_u32 s3, s3, 0x100
	s_addc_u32 s14, s14, 0
	s_cmp_gt_u32 s15, 29
	s_cbranch_scc0 .LBB0_530
	s_and_b64 vcc, exec, s[48:49]
	s_cbranch_vccz .LBB0_533
	s_barrier

; #define PG8_STAGE(bufoff, gbase, voff) do { _Pragma("unroll") for (int _i = 0; _i < 2; ++_i) \
;         __builtin_amdgcn_global_load_lds((const unsigned*)((const char*)(gbase) + (voff)[_i]), (LAS unsigned*)(lds + (bufoff) + ldsw + _i * 8192), 16, 0, 0); } while (0)
; #define PG8_LDA(dst, b, h) do { _Pragma("unroll") for (int m = 0; m < 4; ++m) _Pragma("unroll") for (int k = 0; k < 2; ++k) dst[m][k] = *(const LAS bf16x8*)(lds + PG8_SA(b, h) + aoff + m * 2048 + k * 1024); } while (0)
; #define PG8_LDB(dst, b, h) do { _Pragma("unroll") for (int n = 0; n < 2; ++n) _Pragma("unroll") for (int k = 0; k < 2; ++k) dst[n][k] = *(const LAS bf16x8*)(lds + PG8_SB(b, h) + boff + n * 2048 + k * 1024); } while (0)
; #define PG8_MMA(ai, bj, At, Bt) do { __builtin_amdgcn_s_setprio(1); _Pragma("unroll") for (int m = 0; m < 4; ++m) _Pragma("unroll") for (int n = 0; n < 2; ++n) _Pragma("unroll") for (int k = 0; k < 2; ++k) \
;         acc[ai][bj][m][n] = __builtin_amdgcn_mfma_f32_16x16x32_bf16(Bt[n][k], At[m][k], acc[ai][bj][m][n], 0, 0, 0); __builtin_amdgcn_s_setprio(0); } while (0)
; #define PG8_WAIT_V(n) asm volatile("s_waitcnt vmcnt(" #n ")" ::: "memory")
; #define PG8_WAIT_L(n) asm volatile("s_waitcnt lgkmcnt(" #n ")" ::: "memory")
; #define PG8_BAR __builtin_amdgcn_s_barrier()
; #define PG8_SCHED __builtin_amdgcn_sched_barrier(0)
; template <class Epi, class Sched>
; __device__ __forceinline__ void gemm_phase(LAS unsigned char* lds, const int lda, const int ldb, const int K, const Sched& S, const Epi& E, int tid) {
;     ...
;         for (int t = 0; t < nt; t += 2) {
;             const bool last = (t == nt - 2);
;             const char* a1 = cA + (size_t)(t + 1) * kstep;
;             const char* a2 = last ? nA : cA + (size_t)(t + 2) * kstep; const char* b2 = last ? nB : cB + (size_t)(t + 2) * kstep;
;             const char* a3 = a2 + kstep; const char* b3 = b2 + kstep;
;             PG8_LDB(B0, 0, 0); PG8_LDB(B1, 0, 1); PG8_SCHED; PG8_LDA(At, 0, 0); PG8_STAGE(PG8_SA(1, 1), a1 + hA, voffA);
;             PG8_WAIT_V(8); PG8_WAIT_L(0); PG8_BAR; PG8_MMA(0, 0, At, B0); PG8_MMA(0, 1, At, B1); PG8_BAR; PG8_SCHED;
;             PG8_LDA(At, 0, 1); PG8_STAGE(PG8_SB(0, 0), b2, voffB); PG8_STAGE(PG8_SB(0, 1), b2 + hB, voffB); PG8_STAGE(PG8_SA(0, 0), a2, voffA);
;             PG8_WAIT_V(8); PG8_WAIT_L(0); PG8_BAR; PG8_MMA(1, 0, At, B0); PG8_MMA(1, 1, At, B1); PG8_BAR; PG8_SCHED;
.LBB0_681:
	s_add_u32 s26, s56, 0xfff80080
	s_addc_u32 s27, s57, -1
	s_add_i32 s34, 0, 0x10000
	s_cmp_eq_u32 s60, 28
	s_cselect_b32 vcc_hi, s9, s27
	s_cselect_b32 vcc_lo, s8, s26
	v_add_u32_e32 v0, s34, v198
	s_cselect_b32 s27, s11, s19
	s_cselect_b32 s26, s10, s17
	s_add_i32 s76, 0, 0x14000
	ds_read_b128 v[114:117], v0
	ds_read_b128 v[118:121], v0 offset:1024
	ds_read_b128 v[122:125], v0 offset:2048
	ds_read_b128 v[126:129], v0 offset:3072
	v_add_u32_e32 v0, s76, v198
	ds_read_b128 v[130:133], v0
	ds_read_b128 v[134:137], v0 offset:1024
	ds_read_b128 v[138:141], v0 offset:2048
	ds_read_b128 v[142:145], v0 offset:3072
	s_add_i32 m0, s29, 0xc000
	ds_read_b128 v[162:165], v237
	ds_read_b128 v[166:169], v237 offset:1024
	ds_read_b128 v[202:205], v237 offset:2048
	ds_read_b128 v[206:209], v237 offset:3072
	ds_read_b128 v[210:213], v237 offset:4096
	ds_read_b128 v[214:217], v237 offset:5120
	ds_read_b128 v[218:221], v237 offset:6144
	ds_read_b128 v[240:243], v237 offset:7168
	global_load_lds_dwordx4 v196, s[56:57]
	s_add_i32 m0, s29, 0xe000
	s_nop 0
	global_load_lds_dwordx4 v200, s[56:57]
	s_waitcnt vmcnt(8) lgkmcnt(0)
	s_barrier
	s_setprio 1
	v_mfma_f32_16x16x32_bf16 v[158:161], v[114:117], v[162:165], v[158:161]
	v_mfma_f32_16x16x32_bf16 v[62:65], v[122:125], v[162:165], v[62:65]
	v_mfma_f32_16x16x32_bf16 v[150:153], v[114:117], v[202:205], v[150:153]
	v_mfma_f32_16x16x32_bf16 v[54:57], v[122:125], v[202:205], v[54:57]
	v_mfma_f32_16x16x32_bf16 v[110:113], v[114:117], v[210:213], v[110:113]
	v_mfma_f32_16x16x32_bf16 v[46:49], v[122:125], v[210:213], v[46:49]
	v_mfma_f32_16x16x32_bf16 v[102:105], v[114:117], v[218:221], v[102:105]
	v_mfma_f32_16x16x32_bf16 v[38:41], v[122:125], v[218:221], v[38:41]
	v_mfma_f32_16x16x32_bf16 v[158:161], v[118:121], v[166:169], v[158:161]
	v_mfma_f32_16x16x32_bf16 v[62:65], v[126:129], v[166:169], v[62:65]
	v_mfma_f32_16x16x32_bf16 v[150:153], v[118:121], v[206:209], v[150:153]
	v_mfma_f32_16x16x32_bf16 v[54:57], v[126:129], v[206:209], v[54:57]
	v_mfma_f32_16x16x32_bf16 v[110:113], v[118:121], v[214:217], v[110:113]
	v_mfma_f32_16x16x32_bf16 v[46:49], v[126:129], v[214:217], v[46:49]
	v_mfma_f32_16x16x32_bf16 v[102:105], v[118:121], v[240:243], v[102:105]
	v_mfma_f32_16x16x32_bf16 v[38:41], v[126:129], v[240:243], v[38:41]
	s_setprio 0
	s_setprio 1
	v_mfma_f32_16x16x32_bf16 v[154:157], v[130:133], v[162:165], v[154:157]
	v_mfma_f32_16x16x32_bf16 v[58:61], v[138:141], v[162:165], v[58:61]
	v_mfma_f32_16x16x32_bf16 v[146:149], v[130:133], v[202:205], v[146:149]
	v_mfma_f32_16x16x32_bf16 v[50:53], v[138:141], v[202:205], v[50:53]
	v_mfma_f32_16x16x32_bf16 v[106:109], v[130:133], v[210:213], v[106:109]
	v_mfma_f32_16x16x32_bf16 v[42:45], v[138:141], v[210:213], v[42:45]
	v_mfma_f32_16x16x32_bf16 v[98:101], v[130:133], v[218:221], v[98:101]
	v_mfma_f32_16x16x32_bf16 v[34:37], v[138:141], v[218:221], v[34:37]
	v_mfma_f32_16x16x32_bf16 v[154:157], v[134:137], v[166:169], v[154:157]
	v_mfma_f32_16x16x32_bf16 v[58:61], v[142:145], v[166:169], v[58:61]
	v_mfma_f32_16x16x32_bf16 v[146:149], v[134:137], v[206:209], v[146:149]
	v_mfma_f32_16x16x32_bf16 v[50:53], v[142:145], v[206:209], v[50:53]
	v_mfma_f32_16x16x32_bf16 v[106:109], v[134:137], v[214:217], v[106:109]
	v_mfma_f32_16x16x32_bf16 v[42:45], v[142:145], v[214:217], v[42:45]
	v_mfma_f32_16x16x32_bf16 v[98:101], v[134:137], v[240:243], v[98:101]
	v_mfma_f32_16x16x32_bf16 v[34:37], v[142:145], v[240:243], v[34:37]
	s_setprio 0
	s_barrier
	s_add_i32 s34, s34, s28
	s_mov_b32 m0, s34
	ds_read_b128 v[162:165], v237 offset:16384
	ds_read_b128 v[166:169], v237 offset:17408
	ds_read_b128 v[202:205], v237 offset:18432
	ds_read_b128 v[206:209], v237 offset:19456
	ds_read_b128 v[210:213], v237 offset:20480
	ds_read_b128 v[214:217], v237 offset:21504
	ds_read_b128 v[218:221], v237 offset:22528
	ds_read_b128 v[240:243], v237 offset:23552
	global_load_lds_dwordx4 v172, s[26:27]
	s_add_i32 m0, s34, 0x2000
	s_add_u32 s34, s26, 0x80000
	s_addc_u32 s35, s27, 0
	s_add_i32 s76, s76, s28
	global_load_lds_dwordx4 v176, s[26:27]
	s_mov_b32 m0, s76
	s_nop 0
	global_load_lds_dwordx4 v172, s[34:35]
	s_add_i32 m0, s76, 0x2000
	s_nop 0
	global_load_lds_dwordx4 v176, s[34:35]
	s_mov_b32 m0, s29
	s_nop 0
	global_load_lds_dwordx4 v170, vcc
	s_mov_b32 m0, s67
	s_nop 0
	global_load_lds_dwordx4 v174, vcc
	s_waitcnt vmcnt(8) lgkmcnt(0)
	s_barrier
	s_setprio 1
	v_mfma_f32_16x16x32_bf16 v[94:97], v[114:117], v[162:165], v[94:97]
	v_mfma_f32_16x16x32_bf16 v[30:33], v[122:125], v[162:165], v[30:33]
	v_mfma_f32_16x16x32_bf16 v[86:89], v[114:117], v[202:205], v[86:89]
	v_mfma_f32_16x16x32_bf16 v[22:25], v[122:125], v[202:205], v[22:25]
	v_mfma_f32_16x16x32_bf16 v[78:81], v[114:117], v[210:213], v[78:81]
	v_mfma_f32_16x16x32_bf16 v[14:17], v[122:125], v[210:213], v[14:17]
	v_mfma_f32_16x16x32_bf16 v[70:73], v[114:117], v[218:221], v[70:73]
	v_mfma_f32_16x16x32_bf16 v[6:9], v[122:125], v[218:221], v[6:9]
	v_mfma_f32_16x16x32_bf16 v[94:97], v[118:121], v[166:169], v[94:97]
	v_mfma_f32_16x16x32_bf16 v[30:33], v[126:129], v[166:169], v[30:33]
	v_mfma_f32_16x16x32_bf16 v[86:89], v[118:121], v[206:209], v[86:89]
	v_mfma_f32_16x16x32_bf16 v[22:25], v[126:129], v[206:209], v[22:25]
	v_mfma_f32_16x16x32_bf16 v[78:81], v[118:121], v[214:217], v[78:81]
	v_mfma_f32_16x16x32_bf16 v[14:17], v[126:129], v[214:217], v[14:17]
	v_mfma_f32_16x16x32_bf16 v[70:73], v[118:121], v[240:243], v[70:73]
	v_mfma_f32_16x16x32_bf16 v[6:9], v[126:129], v[240:243], v[6:9]
	s_setprio 0
	s_setprio 1
	v_mfma_f32_16x16x32_bf16 v[90:93], v[130:133], v[162:165], v[90:93]
	v_mfma_f32_16x16x32_bf16 v[26:29], v[138:141], v[162:165], v[26:29]
	v_mfma_f32_16x16x32_bf16 v[82:85], v[130:133], v[202:205], v[82:85]
	v_mfma_f32_16x16x32_bf16 v[18:21], v[138:141], v[202:205], v[18:21]
	v_mfma_f32_16x16x32_bf16 v[74:77], v[130:133], v[210:213], v[74:77]
	v_mfma_f32_16x16x32_bf16 v[10:13], v[138:141], v[210:213], v[10:13]
	v_mfma_f32_16x16x32_bf16 v[66:69], v[130:133], v[218:221], v[66:69]
	v_mfma_f32_16x16x32_bf16 v[2:5], v[138:141], v[218:221], v[2:5]
	v_mfma_f32_16x16x32_bf16 v[90:93], v[134:137], v[166:169], v[90:93]
	v_mfma_f32_16x16x32_bf16 v[26:29], v[142:145], v[166:169], v[26:29]
	v_mfma_f32_16x16x32_bf16 v[82:85], v[134:137], v[206:209], v[82:85]
	v_mfma_f32_16x16x32_bf16 v[18:21], v[142:145], v[206:209], v[18:21]
	v_mfma_f32_16x16x32_bf16 v[74:77], v[134:137], v[214:217], v[74:77]
	v_mfma_f32_16x16x32_bf16 v[10:13], v[142:145], v[214:217], v[10:13]
	v_mfma_f32_16x16x32_bf16 v[66:69], v[134:137], v[240:243], v[66:69]
	v_mfma_f32_16x16x32_bf16 v[2:5], v[142:145], v[240:243], v[2:5]
	s_setprio 0
	s_barrier
; #define PG8_STAGE(bufoff, gbase, voff) do { _Pragma("unroll") for (int _i = 0; _i < 2; ++_i) \
;         __builtin_amdgcn_global_load_lds((const unsigned*)((const char*)(gbase) + (voff)[_i]), (LAS unsigned*)(lds + (bufoff) + ldsw + _i * 8192), 16, 0, 0); } while (0)
; #define PG8_LDA(dst, b, h) do { _Pragma("unroll") for (int m = 0; m < 4; ++m) _Pragma("unroll") for (int k = 0; k < 2; ++k) dst[m][k] = *(const LAS bf16x8*)(lds + PG8_SA(b, h) + aoff + m * 2048 + k * 1024); } while (0)
; #define PG8_LDB(dst, b, h) do { _Pragma("unroll") for (int n = 0; n < 2; ++n) _Pragma("unroll") for (int k = 0; k < 2; ++k) dst[n][k] = *(const LAS bf16x8*)(lds + PG8_SB(b, h) + boff + n * 2048 + k * 1024); } while (0)
; #define PG8_MMA(ai, bj, At, Bt) do { __builtin_amdgcn_s_setprio(1); _Pragma("unroll") for (int m = 0; m < 4; ++m) _Pragma("unroll") for (int n = 0; n < 2; ++n) _Pragma("unroll") for (int k = 0; k < 2; ++k) \
;         acc[ai][bj][m][n] = __builtin_amdgcn_mfma_f32_16x16x32_bf16(Bt[n][k], At[m][k], acc[ai][bj][m][n], 0, 0, 0); __builtin_amdgcn_s_setprio(0); } while (0)
; #define PG8_WAIT_V(n) asm volatile("s_waitcnt vmcnt(" #n ")" ::: "memory")
; #define PG8_WAIT_L(n) asm volatile("s_waitcnt lgkmcnt(" #n ")" ::: "memory")
; #define PG8_BAR __builtin_amdgcn_s_barrier()
; #define PG8_SCHED __builtin_amdgcn_sched_barrier(0)
; template <class Epi, class Sched>
; __device__ __forceinline__ void gemm_phase(LAS unsigned char* lds, const int lda, const int ldb, const int K, const Sched& S, const Epi& E, int tid) {
;     ...
;             PG8_LDB(B0, 1, 0); PG8_LDB(B1, 1, 1); PG8_SCHED; PG8_LDA(At, 1, 0); PG8_STAGE(PG8_SA(0, 1), a2 + hA, voffA);
;             PG8_WAIT_V(8); PG8_WAIT_L(0); PG8_BAR; PG8_MMA(0, 0, At, B0); PG8_MMA(0, 1, At, B1); PG8_BAR; PG8_SCHED;
;             PG8_LDA(At, 1, 1); PG8_STAGE(PG8_SB(1, 0), b3, voffB); PG8_STAGE(PG8_SB(1, 1), b3 + hB, voffB); PG8_STAGE(PG8_SA(1, 0), a3, voffA);
;             PG8_WAIT_V(8); PG8_WAIT_L(0); PG8_BAR; PG8_MMA(1, 0, At, B0); PG8_MMA(1, 1, At, B1); PG8_BAR; PG8_SCHED;
;         }
;         if (wr == 0) PG8_BAR;
	s_add_i32 s76, 0, 0x18000
	v_add_u32_e32 v0, s76, v198
	s_add_i32 s94, 0, 0x1c000
	ds_read_b128 v[114:117], v0
	ds_read_b128 v[118:121], v0 offset:1024
	ds_read_b128 v[122:125], v0 offset:2048
	ds_read_b128 v[126:129], v0 offset:3072
	v_add_u32_e32 v0, s94, v198
	ds_read_b128 v[130:133], v0
	ds_read_b128 v[134:137], v0 offset:1024
	ds_read_b128 v[138:141], v0 offset:2048
	ds_read_b128 v[142:145], v0 offset:3072
	s_add_u32 s34, vcc_lo, 0x80000
	s_addc_u32 s35, vcc_hi, 0
	s_mov_b32 m0, s25
	ds_read_b128 v[162:165], v237 offset:32768
	ds_read_b128 v[166:169], v237 offset:33792
	ds_read_b128 v[202:205], v237 offset:34816
	ds_read_b128 v[206:209], v237 offset:35840
	ds_read_b128 v[210:213], v237 offset:36864
	ds_read_b128 v[214:217], v237 offset:37888
	ds_read_b128 v[218:221], v237 offset:38912
	ds_read_b128 v[240:243], v237 offset:39936
	global_load_lds_dwordx4 v170, s[34:35]
	s_mov_b32 m0, s0
	s_nop 0
	global_load_lds_dwordx4 v174, s[34:35]
	s_waitcnt vmcnt(8) lgkmcnt(0)
	s_barrier
	s_setprio 1
	v_mfma_f32_16x16x32_bf16 v[158:161], v[114:117], v[162:165], v[158:161]
	v_mfma_f32_16x16x32_bf16 v[62:65], v[122:125], v[162:165], v[62:65]
	v_mfma_f32_16x16x32_bf16 v[150:153], v[114:117], v[202:205], v[150:153]
	v_mfma_f32_16x16x32_bf16 v[54:57], v[122:125], v[202:205], v[54:57]
	v_mfma_f32_16x16x32_bf16 v[110:113], v[114:117], v[210:213], v[110:113]
	v_mfma_f32_16x16x32_bf16 v[46:49], v[122:125], v[210:213], v[46:49]
	v_mfma_f32_16x16x32_bf16 v[102:105], v[114:117], v[218:221], v[102:105]
	v_mfma_f32_16x16x32_bf16 v[38:41], v[122:125], v[218:221], v[38:41]
	v_mfma_f32_16x16x32_bf16 v[158:161], v[118:121], v[166:169], v[158:161]
	v_mfma_f32_16x16x32_bf16 v[62:65], v[126:129], v[166:169], v[62:65]
	v_mfma_f32_16x16x32_bf16 v[150:153], v[118:121], v[206:209], v[150:153]
	v_mfma_f32_16x16x32_bf16 v[54:57], v[126:129], v[206:209], v[54:57]
	v_mfma_f32_16x16x32_bf16 v[110:113], v[118:121], v[214:217], v[110:113]
	v_mfma_f32_16x16x32_bf16 v[46:49], v[126:129], v[214:217], v[46:49]
	v_mfma_f32_16x16x32_bf16 v[102:105], v[118:121], v[240:243], v[102:105]
	v_mfma_f32_16x16x32_bf16 v[38:41], v[126:129], v[240:243], v[38:41]
	s_setprio 0
	s_setprio 1
	v_mfma_f32_16x16x32_bf16 v[154:157], v[130:133], v[162:165], v[154:157]
	v_mfma_f32_16x16x32_bf16 v[58:61], v[138:141], v[162:165], v[58:61]
	v_mfma_f32_16x16x32_bf16 v[146:149], v[130:133], v[202:205], v[146:149]
	v_mfma_f32_16x16x32_bf16 v[50:53], v[138:141], v[202:205], v[50:53]
	v_mfma_f32_16x16x32_bf16 v[106:109], v[130:133], v[210:213], v[106:109]
	v_mfma_f32_16x16x32_bf16 v[42:45], v[138:141], v[210:213], v[42:45]
	v_mfma_f32_16x16x32_bf16 v[98:101], v[130:133], v[218:221], v[98:101]
	v_mfma_f32_16x16x32_bf16 v[34:37], v[138:141], v[218:221], v[34:37]
	v_mfma_f32_16x16x32_bf16 v[154:157], v[134:137], v[166:169], v[154:157]
	v_mfma_f32_16x16x32_bf16 v[58:61], v[142:145], v[166:169], v[58:61]
	v_mfma_f32_16x16x32_bf16 v[146:149], v[134:137], v[206:209], v[146:149]
	v_mfma_f32_16x16x32_bf16 v[50:53], v[142:145], v[206:209], v[50:53]
	v_mfma_f32_16x16x32_bf16 v[106:109], v[134:137], v[214:217], v[106:109]
	v_mfma_f32_16x16x32_bf16 v[42:45], v[142:145], v[214:217], v[42:45]
	v_mfma_f32_16x16x32_bf16 v[98:101], v[134:137], v[240:243], v[98:101]
	v_mfma_f32_16x16x32_bf16 v[34:37], v[142:145], v[240:243], v[34:37]
	s_setprio 0
	s_barrier
	s_add_i32 s34, s76, s28
	s_add_u32 s98, s26, s30
	s_addc_u32 s99, s27, s31
	s_mov_b32 m0, s34
	ds_read_b128 v[162:165], v237 offset:49152
	ds_read_b128 v[166:169], v237 offset:50176
	ds_read_b128 v[202:205], v237 offset:51200
	ds_read_b128 v[206:209], v237 offset:52224
	ds_read_b128 v[210:213], v237 offset:53248
	ds_read_b128 v[214:217], v237 offset:54272
	ds_read_b128 v[218:221], v237 offset:55296
	ds_read_b128 v[240:243], v237 offset:56320
	global_load_lds_dwordx4 v172, s[98:99]
	s_add_i32 m0, s34, 0x2000
	s_add_u32 s26, s26, 0x80080
	s_addc_u32 s27, s27, 0
	s_add_i32 s34, s94, s28
	global_load_lds_dwordx4 v176, s[98:99]
	s_mov_b32 m0, s34
	s_nop 0
	global_load_lds_dwordx4 v172, s[26:27]
	s_add_i32 m0, s34, 0x2000
	s_nop 0
	global_load_lds_dwordx4 v176, s[26:27]
	s_add_u32 s100, vcc_lo, s30
	s_addc_u32 s101, vcc_hi, s31
	s_mov_b32 m0, s22
	s_nop 0
	global_load_lds_dwordx4 v170, s[100:101]
	s_mov_b32 m0, s23
	s_nop 0
	global_load_lds_dwordx4 v174, s[100:101]
	s_waitcnt vmcnt(8) lgkmcnt(0)
	s_barrier
	s_setprio 1
	v_mfma_f32_16x16x32_bf16 v[94:97], v[114:117], v[162:165], v[94:97]
	v_mfma_f32_16x16x32_bf16 v[30:33], v[122:125], v[162:165], v[30:33]
	v_mfma_f32_16x16x32_bf16 v[86:89], v[114:117], v[202:205], v[86:89]
	v_mfma_f32_16x16x32_bf16 v[22:25], v[122:125], v[202:205], v[22:25]
	v_mfma_f32_16x16x32_bf16 v[78:81], v[114:117], v[210:213], v[78:81]
	v_mfma_f32_16x16x32_bf16 v[14:17], v[122:125], v[210:213], v[14:17]
	v_mfma_f32_16x16x32_bf16 v[70:73], v[114:117], v[218:221], v[70:73]
	v_mfma_f32_16x16x32_bf16 v[6:9], v[122:125], v[218:221], v[6:9]
	v_mfma_f32_16x16x32_bf16 v[94:97], v[118:121], v[166:169], v[94:97]
	v_mfma_f32_16x16x32_bf16 v[30:33], v[126:129], v[166:169], v[30:33]
	v_mfma_f32_16x16x32_bf16 v[86:89], v[118:121], v[206:209], v[86:89]
	v_mfma_f32_16x16x32_bf16 v[22:25], v[126:129], v[206:209], v[22:25]
	v_mfma_f32_16x16x32_bf16 v[78:81], v[118:121], v[214:217], v[78:81]
	v_mfma_f32_16x16x32_bf16 v[14:17], v[126:129], v[214:217], v[14:17]
	v_mfma_f32_16x16x32_bf16 v[70:73], v[118:121], v[240:243], v[70:73]
	v_mfma_f32_16x16x32_bf16 v[6:9], v[126:129], v[240:243], v[6:9]
	s_setprio 0
	s_setprio 1
	v_mfma_f32_16x16x32_bf16 v[90:93], v[130:133], v[162:165], v[90:93]
	v_mfma_f32_16x16x32_bf16 v[26:29], v[138:141], v[162:165], v[26:29]
	v_mfma_f32_16x16x32_bf16 v[82:85], v[130:133], v[202:205], v[82:85]
	v_mfma_f32_16x16x32_bf16 v[18:21], v[138:141], v[202:205], v[18:21]
	v_mfma_f32_16x16x32_bf16 v[74:77], v[130:133], v[210:213], v[74:77]
	v_mfma_f32_16x16x32_bf16 v[10:13], v[138:141], v[210:213], v[10:13]
	v_mfma_f32_16x16x32_bf16 v[66:69], v[130:133], v[218:221], v[66:69]
	v_mfma_f32_16x16x32_bf16 v[2:5], v[138:141], v[218:221], v[2:5]
	v_mfma_f32_16x16x32_bf16 v[90:93], v[134:137], v[166:169], v[90:93]
	v_mfma_f32_16x16x32_bf16 v[26:29], v[142:145], v[166:169], v[26:29]
	v_mfma_f32_16x16x32_bf16 v[82:85], v[134:137], v[206:209], v[82:85]
	v_mfma_f32_16x16x32_bf16 v[18:21], v[142:145], v[206:209], v[18:21]
	v_mfma_f32_16x16x32_bf16 v[74:77], v[134:137], v[214:217], v[74:77]
	v_mfma_f32_16x16x32_bf16 v[10:13], v[142:145], v[214:217], v[10:13]
	v_mfma_f32_16x16x32_bf16 v[66:69], v[134:137], v[240:243], v[66:69]
	v_mfma_f32_16x16x32_bf16 v[2:5], v[142:145], v[240:243], v[2:5]
	s_setprio 0
	s_barrier
	s_add_i32 s60, s60, 2
	s_add_u32 s56, s56, 0x100
	s_addc_u32 s57, s57, 0
	s_add_u32 s17, s17, 0x100
	s_addc_u32 s19, s19, 0
	s_cmp_gt_u32 s60, 29
	s_cbranch_scc0 .LBB0_681
	s_and_b64 vcc, exec, s[90:91]
	s_cbranch_vccz .LBB0_686
	s_barrier
	s_and_saveexec_b64 s[26:27], s[40:41]
	s_movk_i32 s60, 0x2c00
	s_cbranch_execnz .LBB0_687

; #define PG8_STAGE(bufoff, gbase, voff) do { _Pragma("unroll") for (int _i = 0; _i < 2; ++_i) \
;         __builtin_amdgcn_global_load_lds((const unsigned*)((const char*)(gbase) + (voff)[_i]), (LAS unsigned*)(lds + (bufoff) + ldsw + _i * 8192), 16, 0, 0); } while (0)
; #define PG8_LDA(dst, b, h) do { _Pragma("unroll") for (int m = 0; m < 4; ++m) _Pragma("unroll") for (int k = 0; k < 2; ++k) dst[m][k] = *(const LAS bf16x8*)(lds + PG8_SA(b, h) + aoff + m * 2048 + k * 1024); } while (0)
; #define PG8_LDB(dst, b, h) do { _Pragma("unroll") for (int n = 0; n < 2; ++n) _Pragma("unroll") for (int k = 0; k < 2; ++k) dst[n][k] = *(const LAS bf16x8*)(lds + PG8_SB(b, h) + boff + n * 2048 + k * 1024); } while (0)
; #define PG8_MMA(ai, bj, At, Bt) do { __builtin_amdgcn_s_setprio(1); _Pragma("unroll") for (int m = 0; m < 4; ++m) _Pragma("unroll") for (int n = 0; n < 2; ++n) _Pragma("unroll") for (int k = 0; k < 2; ++k) \
;         acc[ai][bj][m][n] = __builtin_amdgcn_mfma_f32_16x16x32_bf16(Bt[n][k], At[m][k], acc[ai][bj][m][n], 0, 0, 0); __builtin_amdgcn_s_setprio(0); } while (0)
; #define PG8_WAIT_V(n) asm volatile("s_waitcnt vmcnt(" #n ")" ::: "memory")
; #define PG8_WAIT_L(n) asm volatile("s_waitcnt lgkmcnt(" #n ")" ::: "memory")
; #define PG8_BAR __builtin_amdgcn_s_barrier()
; #define PG8_SCHED __builtin_amdgcn_sched_barrier(0)
; template <class Epi, class Sched>
; __device__ __forceinline__ void gemm_phase(LAS unsigned char* lds, const int lda, const int ldb, const int K, const Sched& S, const Epi& E, int tid) {
;     ...
;         for (int t = 0; t < nt; t += 2) {
;             const bool last = (t == nt - 2);
;             const char* a1 = cA + (size_t)(t + 1) * kstep;
;             const char* a2 = last ? nA : cA + (size_t)(t + 2) * kstep; const char* b2 = last ? nB : cB + (size_t)(t + 2) * kstep;
;             const char* a3 = a2 + kstep; const char* b3 = b2 + kstep;
;             PG8_LDB(B0, 0, 0); PG8_LDB(B1, 0, 1); PG8_SCHED; PG8_LDA(At, 0, 0); PG8_STAGE(PG8_SA(1, 1), a1 + hA, voffA);
;             PG8_WAIT_V(8); PG8_WAIT_L(0); PG8_BAR; PG8_MMA(0, 0, At, B0); PG8_MMA(0, 1, At, B1); PG8_BAR; PG8_SCHED;
;             PG8_LDA(At, 0, 1); PG8_STAGE(PG8_SB(0, 0), b2, voffB); PG8_STAGE(PG8_SB(0, 1), b2 + hB, voffB); PG8_STAGE(PG8_SA(0, 0), a2, voffA);
;             PG8_WAIT_V(8); PG8_WAIT_L(0); PG8_BAR; PG8_MMA(1, 0, At, B0); PG8_MMA(1, 1, At, B1); PG8_BAR; PG8_SCHED;
.LBB0_880:
	s_add_u32 s4, s2, 0x100
	s_addc_u32 s5, s3, 0
	s_add_i32 s33, 0, 0x10000
	s_cmpk_eq_i32 s29, 0x54
	s_cselect_b32 s9, s49, s5
	s_cselect_b32 s8, s48, s4
	s_cselect_b32 s7, s51, s28
	s_cselect_b32 s6, s50, s25
	s_add_i32 s34, 0, 0x14000
	v_add_u32_e32 v130, s33, v208
	v_add_u32_e32 v168, s34, v208
	ds_read_b128 v[82:85], v130
	ds_read_b128 v[86:89], v130 offset:1024
	ds_read_b128 v[126:129], v130 offset:2048
	ds_read_b128 v[130:133], v130 offset:3072
	ds_read_b128 v[156:159], v168
	ds_read_b128 v[160:163], v168 offset:1024
	ds_read_b128 v[164:167], v168 offset:2048
	ds_read_b128 v[168:171], v168 offset:3072
	s_add_i32 m0, s15, 0xc000
	ds_read_b128 v[172:175], v210
	ds_read_b128 v[176:179], v210 offset:1024
	ds_read_b128 v[180:183], v210 offset:2048
	ds_read_b128 v[184:187], v210 offset:3072
	ds_read_b128 v[188:191], v210 offset:4096
	ds_read_b128 v[192:195], v210 offset:5120
	ds_read_b128 v[200:203], v210 offset:6144
	ds_read_b128 v[204:207], v210 offset:7168
	global_load_lds_dwordx4 v152, s[2:3]
	s_add_i32 m0, s15, 0xe000
	s_nop 0
	global_load_lds_dwordx4 v154, s[2:3]
	s_waitcnt vmcnt(8) lgkmcnt(0)
	s_barrier
	s_setprio 1
	v_mfma_f32_16x16x32_bf16 v[142:145], v[82:85], v[172:175], v[142:145]
	v_mfma_f32_16x16x32_bf16 v[102:105], v[126:129], v[172:175], v[102:105]
	v_mfma_f32_16x16x32_bf16 v[138:141], v[82:85], v[180:183], v[138:141]
	v_mfma_f32_16x16x32_bf16 v[98:101], v[126:129], v[180:183], v[98:101]
	v_mfma_f32_16x16x32_bf16 v[134:137], v[82:85], v[188:191], v[134:137]
	v_mfma_f32_16x16x32_bf16 v[94:97], v[126:129], v[188:191], v[94:97]
	v_mfma_f32_16x16x32_bf16 v[122:125], v[82:85], v[200:203], v[122:125]
	v_mfma_f32_16x16x32_bf16 v[90:93], v[126:129], v[200:203], v[90:93]
	v_mfma_f32_16x16x32_bf16 v[142:145], v[86:89], v[176:179], v[142:145]
	v_mfma_f32_16x16x32_bf16 v[102:105], v[130:133], v[176:179], v[102:105]
	v_mfma_f32_16x16x32_bf16 v[138:141], v[86:89], v[184:187], v[138:141]
	v_mfma_f32_16x16x32_bf16 v[98:101], v[130:133], v[184:187], v[98:101]
	v_mfma_f32_16x16x32_bf16 v[134:137], v[86:89], v[192:195], v[134:137]
	v_mfma_f32_16x16x32_bf16 v[94:97], v[130:133], v[192:195], v[94:97]
	v_mfma_f32_16x16x32_bf16 v[122:125], v[86:89], v[204:207], v[122:125]
	v_mfma_f32_16x16x32_bf16 v[90:93], v[130:133], v[204:207], v[90:93]
	s_setprio 0
	s_setprio 1
	v_mfma_f32_16x16x32_bf16 v[66:69], v[156:159], v[172:175], v[66:69]
	v_mfma_f32_16x16x32_bf16 v[34:37], v[164:167], v[172:175], v[34:37]
	v_mfma_f32_16x16x32_bf16 v[58:61], v[156:159], v[180:183], v[58:61]
	v_mfma_f32_16x16x32_bf16 v[26:29], v[164:167], v[180:183], v[26:29]
	v_mfma_f32_16x16x32_bf16 v[54:57], v[156:159], v[188:191], v[54:57]
	v_mfma_f32_16x16x32_bf16 v[22:25], v[164:167], v[188:191], v[22:25]
	v_mfma_f32_16x16x32_bf16 v[50:53], v[156:159], v[200:203], v[50:53]
	v_mfma_f32_16x16x32_bf16 v[18:21], v[164:167], v[200:203], v[18:21]
	v_mfma_f32_16x16x32_bf16 v[66:69], v[160:163], v[176:179], v[66:69]
	v_mfma_f32_16x16x32_bf16 v[34:37], v[168:171], v[176:179], v[34:37]
	v_mfma_f32_16x16x32_bf16 v[58:61], v[160:163], v[184:187], v[58:61]
	v_mfma_f32_16x16x32_bf16 v[26:29], v[168:171], v[184:187], v[26:29]
	v_mfma_f32_16x16x32_bf16 v[54:57], v[160:163], v[192:195], v[54:57]
	v_mfma_f32_16x16x32_bf16 v[22:25], v[168:171], v[192:195], v[22:25]
	v_mfma_f32_16x16x32_bf16 v[50:53], v[160:163], v[204:207], v[50:53]
	v_mfma_f32_16x16x32_bf16 v[18:21], v[168:171], v[204:207], v[18:21]
	s_setprio 0
	s_barrier
	s_add_u32 s98, s6, s30
	s_addc_u32 s99, s7, s31
	s_add_u32 s100, s8, s30
	s_addc_u32 s101, s9, s31
	s_add_i32 s2, s33, s14
	s_mov_b32 m0, s2
	ds_read_b128 v[172:175], v210 offset:16384
	ds_read_b128 v[176:179], v210 offset:17408
	ds_read_b128 v[180:183], v210 offset:18432
	ds_read_b128 v[184:187], v210 offset:19456
	ds_read_b128 v[188:191], v210 offset:20480
	ds_read_b128 v[192:195], v210 offset:21504
	ds_read_b128 v[200:203], v210 offset:22528
	ds_read_b128 v[204:207], v210 offset:23552
	global_load_lds_dwordx4 v0, s[6:7]
	s_add_i32 m0, s2, 0x2000
	s_add_u32 s2, s6, 0x160000
	s_addc_u32 s3, s7, 0
	s_add_i32 s33, s34, s14
	global_load_lds_dwordx4 v150, s[6:7]
	s_mov_b32 m0, s33
	s_nop 0
	global_load_lds_dwordx4 v0, s[2:3]
	s_add_i32 m0, s33, 0x2000
	s_nop 0
	global_load_lds_dwordx4 v150, s[2:3]
	s_mov_b32 m0, s15
	s_nop 0
	global_load_lds_dwordx4 v146, s[8:9]
	s_mov_b32 m0, s16
	s_nop 0
	global_load_lds_dwordx4 v148, s[8:9]
	s_waitcnt vmcnt(8) lgkmcnt(0)
	s_barrier
	s_setprio 1
	v_mfma_f32_16x16x32_bf16 v[118:121], v[82:85], v[172:175], v[118:121]
	v_mfma_f32_16x16x32_bf16 v[78:81], v[126:129], v[172:175], v[78:81]
	v_mfma_f32_16x16x32_bf16 v[114:117], v[82:85], v[180:183], v[114:117]
	v_mfma_f32_16x16x32_bf16 v[74:77], v[126:129], v[180:183], v[74:77]
	v_mfma_f32_16x16x32_bf16 v[110:113], v[82:85], v[188:191], v[110:113]
	v_mfma_f32_16x16x32_bf16 v[70:73], v[126:129], v[188:191], v[70:73]
	v_mfma_f32_16x16x32_bf16 v[62:65], v[126:129], v[200:203], v[62:65]
	v_mfma_f32_16x16x32_bf16 v[118:121], v[86:89], v[176:179], v[118:121]
	v_mfma_f32_16x16x32_bf16 v[78:81], v[130:133], v[176:179], v[78:81]
	v_mfma_f32_16x16x32_bf16 v[114:117], v[86:89], v[184:187], v[114:117]
	v_mfma_f32_16x16x32_bf16 v[74:77], v[130:133], v[184:187], v[74:77]
	v_mfma_f32_16x16x32_bf16 v[110:113], v[86:89], v[192:195], v[110:113]
	v_mfma_f32_16x16x32_bf16 v[70:73], v[130:133], v[192:195], v[70:73]
	v_mfma_f32_16x16x32_bf16 v[82:85], v[82:85], v[200:203], v[106:109]
	v_mfma_f32_16x16x32_bf16 v[62:65], v[130:133], v[204:207], v[62:65]
	v_mfma_f32_16x16x32_bf16 v[82:85], v[86:89], v[204:207], v[82:85]
	s_setprio 0
	s_setprio 1
	v_mfma_f32_16x16x32_bf16 v[46:49], v[156:159], v[172:175], v[46:49]
	v_mfma_f32_16x16x32_bf16 v[14:17], v[164:167], v[172:175], v[14:17]
	v_mfma_f32_16x16x32_bf16 v[42:45], v[156:159], v[180:183], v[42:45]
	v_mfma_f32_16x16x32_bf16 v[10:13], v[164:167], v[180:183], v[10:13]
	v_mfma_f32_16x16x32_bf16 v[38:41], v[156:159], v[188:191], v[38:41]
	v_mfma_f32_16x16x32_bf16 v[6:9], v[164:167], v[188:191], v[6:9]
	v_mfma_f32_16x16x32_bf16 v[30:33], v[156:159], v[200:203], v[30:33]
	v_mfma_f32_16x16x32_bf16 v[2:5], v[164:167], v[200:203], v[2:5]
	v_mfma_f32_16x16x32_bf16 v[46:49], v[160:163], v[176:179], v[46:49]
	v_mfma_f32_16x16x32_bf16 v[14:17], v[168:171], v[176:179], v[14:17]
	v_mfma_f32_16x16x32_bf16 v[42:45], v[160:163], v[184:187], v[42:45]
	v_mfma_f32_16x16x32_bf16 v[10:13], v[168:171], v[184:187], v[10:13]
	v_mfma_f32_16x16x32_bf16 v[38:41], v[160:163], v[192:195], v[38:41]
	v_mfma_f32_16x16x32_bf16 v[6:9], v[168:171], v[192:195], v[6:9]
	v_mfma_f32_16x16x32_bf16 v[30:33], v[160:163], v[204:207], v[30:33]
	v_mfma_f32_16x16x32_bf16 v[2:5], v[168:171], v[204:207], v[2:5]
	s_setprio 0
	s_barrier
; #define PG8_STAGE(bufoff, gbase, voff) do { _Pragma("unroll") for (int _i = 0; _i < 2; ++_i) \
;         __builtin_amdgcn_global_load_lds((const unsigned*)((const char*)(gbase) + (voff)[_i]), (LAS unsigned*)(lds + (bufoff) + ldsw + _i * 8192), 16, 0, 0); } while (0)
; #define PG8_LDA(dst, b, h) do { _Pragma("unroll") for (int m = 0; m < 4; ++m) _Pragma("unroll") for (int k = 0; k < 2; ++k) dst[m][k] = *(const LAS bf16x8*)(lds + PG8_SA(b, h) + aoff + m * 2048 + k * 1024); } while (0)
; #define PG8_LDB(dst, b, h) do { _Pragma("unroll") for (int n = 0; n < 2; ++n) _Pragma("unroll") for (int k = 0; k < 2; ++k) dst[n][k] = *(const LAS bf16x8*)(lds + PG8_SB(b, h) + boff + n * 2048 + k * 1024); } while (0)
; #define PG8_MMA(ai, bj, At, Bt) do { __builtin_amdgcn_s_setprio(1); _Pragma("unroll") for (int m = 0; m < 4; ++m) _Pragma("unroll") for (int n = 0; n < 2; ++n) _Pragma("unroll") for (int k = 0; k < 2; ++k) \
;         acc[ai][bj][m][n] = __builtin_amdgcn_mfma_f32_16x16x32_bf16(Bt[n][k], At[m][k], acc[ai][bj][m][n], 0, 0, 0); __builtin_amdgcn_s_setprio(0); } while (0)
; #define PG8_WAIT_V(n) asm volatile("s_waitcnt vmcnt(" #n ")" ::: "memory")
; #define PG8_WAIT_L(n) asm volatile("s_waitcnt lgkmcnt(" #n ")" ::: "memory")
; #define PG8_BAR __builtin_amdgcn_s_barrier()
; #define PG8_SCHED __builtin_amdgcn_sched_barrier(0)
; template <class Epi, class Sched>
; __device__ __forceinline__ void gemm_phase(LAS unsigned char* lds, const int lda, const int ldb, const int K, const Sched& S, const Epi& E, int tid) {
;     ...
;             PG8_LDB(B0, 1, 0); PG8_LDB(B1, 1, 1); PG8_SCHED; PG8_LDA(At, 1, 0); PG8_STAGE(PG8_SA(0, 1), a2 + hA, voffA);
;             PG8_WAIT_V(8); PG8_WAIT_L(0); PG8_BAR; PG8_MMA(0, 0, At, B0); PG8_MMA(0, 1, At, B1); PG8_BAR; PG8_SCHED;
;             PG8_LDA(At, 1, 1); PG8_STAGE(PG8_SB(1, 0), b3, voffB); PG8_STAGE(PG8_SB(1, 1), b3 + hB, voffB); PG8_STAGE(PG8_SA(1, 0), a3, voffA);
;             PG8_WAIT_V(8); PG8_WAIT_L(0); PG8_BAR; PG8_MMA(1, 0, At, B0); PG8_MMA(1, 1, At, B1); PG8_BAR; PG8_SCHED;
;         }
;         if (wr == 0) PG8_BAR;
	s_add_i32 s33, 0, 0x18000
	s_add_i32 s34, 0, 0x1c000
	v_add_u32_e32 v130, s33, v208
	v_add_u32_e32 v168, s34, v208
	ds_read_b128 v[86:89], v130
	ds_read_b128 v[106:109], v130 offset:1024
	ds_read_b128 v[126:129], v130 offset:2048
	ds_read_b128 v[130:133], v130 offset:3072
	ds_read_b128 v[156:159], v168
	ds_read_b128 v[160:163], v168 offset:1024
	ds_read_b128 v[164:167], v168 offset:2048
	ds_read_b128 v[168:171], v168 offset:3072
	s_add_u32 s2, s8, 0x160000
	s_addc_u32 s3, s9, 0
	s_mov_b32 m0, s17
	ds_read_b128 v[172:175], v210 offset:32768
	ds_read_b128 v[176:179], v210 offset:33792
	ds_read_b128 v[180:183], v210 offset:34816
	ds_read_b128 v[184:187], v210 offset:35840
	ds_read_b128 v[188:191], v210 offset:36864
	ds_read_b128 v[192:195], v210 offset:37888
	ds_read_b128 v[200:203], v210 offset:38912
	ds_read_b128 v[204:207], v210 offset:39936
	global_load_lds_dwordx4 v146, s[2:3]
	s_mov_b32 m0, s18
	s_nop 0
	global_load_lds_dwordx4 v148, s[2:3]
	s_waitcnt vmcnt(8) lgkmcnt(0)
	s_barrier
	s_setprio 1
	v_mfma_f32_16x16x32_bf16 v[142:145], v[86:89], v[172:175], v[142:145]
	v_mfma_f32_16x16x32_bf16 v[102:105], v[126:129], v[172:175], v[102:105]
	v_mfma_f32_16x16x32_bf16 v[138:141], v[86:89], v[180:183], v[138:141]
	v_mfma_f32_16x16x32_bf16 v[98:101], v[126:129], v[180:183], v[98:101]
	v_mfma_f32_16x16x32_bf16 v[134:137], v[86:89], v[188:191], v[134:137]
	v_mfma_f32_16x16x32_bf16 v[94:97], v[126:129], v[188:191], v[94:97]
	v_mfma_f32_16x16x32_bf16 v[122:125], v[86:89], v[200:203], v[122:125]
	v_mfma_f32_16x16x32_bf16 v[90:93], v[126:129], v[200:203], v[90:93]
	v_mfma_f32_16x16x32_bf16 v[142:145], v[106:109], v[176:179], v[142:145]
	v_mfma_f32_16x16x32_bf16 v[102:105], v[130:133], v[176:179], v[102:105]
	v_mfma_f32_16x16x32_bf16 v[138:141], v[106:109], v[184:187], v[138:141]
	v_mfma_f32_16x16x32_bf16 v[98:101], v[130:133], v[184:187], v[98:101]
	v_mfma_f32_16x16x32_bf16 v[134:137], v[106:109], v[192:195], v[134:137]
	v_mfma_f32_16x16x32_bf16 v[94:97], v[130:133], v[192:195], v[94:97]
	v_mfma_f32_16x16x32_bf16 v[122:125], v[106:109], v[204:207], v[122:125]
	v_mfma_f32_16x16x32_bf16 v[90:93], v[130:133], v[204:207], v[90:93]
	s_setprio 0
	s_setprio 1
	v_mfma_f32_16x16x32_bf16 v[66:69], v[156:159], v[172:175], v[66:69]
	v_mfma_f32_16x16x32_bf16 v[34:37], v[164:167], v[172:175], v[34:37]
	v_mfma_f32_16x16x32_bf16 v[58:61], v[156:159], v[180:183], v[58:61]
	v_mfma_f32_16x16x32_bf16 v[26:29], v[164:167], v[180:183], v[26:29]
	v_mfma_f32_16x16x32_bf16 v[54:57], v[156:159], v[188:191], v[54:57]
	v_mfma_f32_16x16x32_bf16 v[22:25], v[164:167], v[188:191], v[22:25]
	v_mfma_f32_16x16x32_bf16 v[50:53], v[156:159], v[200:203], v[50:53]
	v_mfma_f32_16x16x32_bf16 v[18:21], v[164:167], v[200:203], v[18:21]
	v_mfma_f32_16x16x32_bf16 v[66:69], v[160:163], v[176:179], v[66:69]
	v_mfma_f32_16x16x32_bf16 v[34:37], v[168:171], v[176:179], v[34:37]
	v_mfma_f32_16x16x32_bf16 v[58:61], v[160:163], v[184:187], v[58:61]
	v_mfma_f32_16x16x32_bf16 v[26:29], v[168:171], v[184:187], v[26:29]
	v_mfma_f32_16x16x32_bf16 v[54:57], v[160:163], v[192:195], v[54:57]
	v_mfma_f32_16x16x32_bf16 v[22:25], v[168:171], v[192:195], v[22:25]
	v_mfma_f32_16x16x32_bf16 v[50:53], v[160:163], v[204:207], v[50:53]
	v_mfma_f32_16x16x32_bf16 v[18:21], v[168:171], v[204:207], v[18:21]
	s_setprio 0
	s_barrier
	s_add_i32 s2, s33, s14
	s_mov_b32 m0, s2
	ds_read_b128 v[172:175], v210 offset:49152
	ds_read_b128 v[176:179], v210 offset:50176
	ds_read_b128 v[180:183], v210 offset:51200
	ds_read_b128 v[184:187], v210 offset:52224
	ds_read_b128 v[188:191], v210 offset:53248
	ds_read_b128 v[192:195], v210 offset:54272
	ds_read_b128 v[200:203], v210 offset:55296
	ds_read_b128 v[204:207], v210 offset:56320
	global_load_lds_dwordx4 v0, s[98:99]
	s_add_i32 m0, s2, 0x2000
	s_add_u32 s2, s6, 0x160080
	s_addc_u32 s3, s7, 0
	s_add_i32 s6, s34, s14
	global_load_lds_dwordx4 v150, s[98:99]
	s_mov_b32 m0, s6
	s_nop 0
	global_load_lds_dwordx4 v0, s[2:3]
	s_add_i32 m0, s6, 0x2000
	s_nop 0
	global_load_lds_dwordx4 v150, s[2:3]
	s_mov_b32 m0, s19
	s_nop 0
	global_load_lds_dwordx4 v146, s[100:101]
	s_mov_b32 m0, s20
	s_nop 0
	global_load_lds_dwordx4 v148, s[100:101]
	s_waitcnt vmcnt(8) lgkmcnt(0)
	s_barrier
	s_setprio 1
	v_mfma_f32_16x16x32_bf16 v[118:121], v[86:89], v[172:175], v[118:121]
	v_mfma_f32_16x16x32_bf16 v[78:81], v[126:129], v[172:175], v[78:81]
	v_mfma_f32_16x16x32_bf16 v[114:117], v[86:89], v[180:183], v[114:117]
	v_mfma_f32_16x16x32_bf16 v[74:77], v[126:129], v[180:183], v[74:77]
	v_mfma_f32_16x16x32_bf16 v[110:113], v[86:89], v[188:191], v[110:113]
	v_mfma_f32_16x16x32_bf16 v[70:73], v[126:129], v[188:191], v[70:73]
	v_mfma_f32_16x16x32_bf16 v[82:85], v[86:89], v[200:203], v[82:85]
	v_mfma_f32_16x16x32_bf16 v[62:65], v[126:129], v[200:203], v[62:65]
	v_mfma_f32_16x16x32_bf16 v[118:121], v[106:109], v[176:179], v[118:121]
	v_mfma_f32_16x16x32_bf16 v[78:81], v[130:133], v[176:179], v[78:81]
	v_mfma_f32_16x16x32_bf16 v[114:117], v[106:109], v[184:187], v[114:117]
	v_mfma_f32_16x16x32_bf16 v[74:77], v[130:133], v[184:187], v[74:77]
	v_mfma_f32_16x16x32_bf16 v[110:113], v[106:109], v[192:195], v[110:113]
	v_mfma_f32_16x16x32_bf16 v[70:73], v[130:133], v[192:195], v[70:73]
	v_mfma_f32_16x16x32_bf16 v[106:109], v[106:109], v[204:207], v[82:85]
	v_mfma_f32_16x16x32_bf16 v[62:65], v[130:133], v[204:207], v[62:65]
	s_setprio 0
	s_setprio 1
	v_mfma_f32_16x16x32_bf16 v[46:49], v[156:159], v[172:175], v[46:49]
	v_mfma_f32_16x16x32_bf16 v[14:17], v[164:167], v[172:175], v[14:17]
	v_mfma_f32_16x16x32_bf16 v[42:45], v[156:159], v[180:183], v[42:45]
	v_mfma_f32_16x16x32_bf16 v[10:13], v[164:167], v[180:183], v[10:13]
	v_mfma_f32_16x16x32_bf16 v[38:41], v[156:159], v[188:191], v[38:41]
	v_mfma_f32_16x16x32_bf16 v[6:9], v[164:167], v[188:191], v[6:9]
	v_mfma_f32_16x16x32_bf16 v[30:33], v[156:159], v[200:203], v[30:33]
	v_mfma_f32_16x16x32_bf16 v[2:5], v[164:167], v[200:203], v[2:5]
	v_mfma_f32_16x16x32_bf16 v[46:49], v[160:163], v[176:179], v[46:49]
	v_mfma_f32_16x16x32_bf16 v[14:17], v[168:171], v[176:179], v[14:17]
	v_mfma_f32_16x16x32_bf16 v[42:45], v[160:163], v[184:187], v[42:45]
	v_mfma_f32_16x16x32_bf16 v[10:13], v[168:171], v[184:187], v[10:13]
	v_mfma_f32_16x16x32_bf16 v[38:41], v[160:163], v[192:195], v[38:41]
	v_mfma_f32_16x16x32_bf16 v[6:9], v[168:171], v[192:195], v[6:9]
	v_mfma_f32_16x16x32_bf16 v[30:33], v[160:163], v[204:207], v[30:33]
	v_mfma_f32_16x16x32_bf16 v[2:5], v[168:171], v[204:207], v[2:5]
	s_setprio 0
	s_barrier
	s_add_i32 s29, s29, 2
	s_add_u32 s25, s25, 0x100
	s_addc_u32 s28, s28, 0
	s_cmpk_gt_u32 s29, 0x55
	s_mov_b64 s[2:3], s[4:5]
	s_cbranch_scc0 .LBB0_880
	s_and_b64 vcc, exec, s[46:47]
	s_cbranch_vccz .LBB0_883
	s_barrier
